# stick-breaking tile loop: wave-uniform fast path for tiles where every active lane is fully inside the causal range (skips per-element index/compare/select masking; same math)
# speedup vs baseline: 1.0058x; 1.0058x over previous
; DI int crow(int reg, int hh) { return (reg & 3) + 8 * (reg >> 2) + 4 * hh; }
; DI float ex2(float x) { return __builtin_amdgcn_exp2f(x); }
; DI void sb_item(const bf16_t* __restrict__ P, const bf16_t* __restrict__ VT, bf16_t* __restrict__ Y, int item, char* lds) {
;     ...
;   auto do_tile = [&](int kb, const bf16_t* kcur) {
;     const bool active = (kb * 64 < q0 + 31) && (__ballot(carry > 0.f) != 0ull);
;     if (active) {
;       qk_tile(kcur, qf, S, l32, hh);
;       const bool full = kb * 64 + 63 < q0;
; #pragma unroll
;     ...
;         float st[16];
; #pragma unroll
;         for (int e = 0; e < 16; ++e) {
;           const float ez = ex2(S[kt2][e]);
;           const float r = __builtin_amdgcn_rcpf(1.f + ez);
;           const bool vis = full || (kb * 64 + kt2 * 32 + crow(e, hh) < qpos);
;           st[e] = vis ? r : 1.f;
;           S[kt2][e] = vis ? 1.f - r : 0.f;
;         }
;     ...
;   for (int kb = kbs; kb >= 1; kb -= 2) {
;     const bf16_t* bcur = Ks + par * (4 * TS);
;     bf16_t* bnxt = Ks + (par ^ 1) * (4 * TS);
;     tile_commit(bnxt, pfk); tile_commit(bnxt + TS, pfv); tile_commit(bnxt + 2 * TS, pfk1); tile_commit(bnxt + 3 * TS, pfv1);
;     {
;       const int f0 = kb >= 5 ? kb - 4 : 1, f1 = kb >= 5 ? kb - 5 : 0;
;       pfk = tile_fetch(kb0 + (size_t)f0 * 64 * LDP_O, LDP_O); pfv = tile_fetch(vb0 + f0 * 64, SEQ);
;       pfk1 = tile_fetch(kb0 + (size_t)f1 * 64 * LDP_O, LDP_O); pfv1 = tile_fetch(vb0 + f1 * 64, SEQ);
;       __builtin_amdgcn_sched_barrier(0); }
.LBB0_485:
	v_mov_b32_e32 v0, v167
	s_mul_i32 s14, s12, 0x9000
	s_xor_b32 s12, s12, 1
	v_lshrrev_b32_e32 v2, 3, v0
	v_lshlrev_b32_e32 v0, 4, v0
	s_mul_i32 s0, s12, 0x9000
	v_mul_lo_u32 v2, v2, s92
	v_and_b32_e32 v0, 0x70, v0
	v_add3_u32 v0, s0, v2, v0
	s_waitcnt vmcnt(3)
	ds_write_b128 v0, v[96:99]
	v_mov_b32_e32 v0, v167
	s_add_i32 s9, s9, -2
	v_lshrrev_b32_e32 v2, 3, v0
	v_lshlrev_b32_e32 v0, 4, v0
	v_mul_lo_u32 v2, v2, s92
	v_and_b32_e32 v0, 0x70, v0
	v_add3_u32 v0, s0, v2, v0
	s_waitcnt vmcnt(2)
	ds_write_b128 v0, v[100:103] offset:9216
	v_mov_b32_e32 v0, v167
	v_mov_b32_e32 v3, v1
	v_lshrrev_b32_e32 v2, 3, v0
	v_lshlrev_b32_e32 v0, 4, v0
	v_mul_lo_u32 v2, v2, s92
	v_and_b32_e32 v0, 0x70, v0
	v_add3_u32 v0, s0, v2, v0
	s_waitcnt vmcnt(1)
	ds_write_b128 v0, v[104:107] offset:18432
	v_mov_b32_e32 v0, v167
	s_nop 0
	v_lshrrev_b32_e32 v2, 3, v0
	v_lshlrev_b32_e32 v0, 4, v0
	v_mul_lo_u32 v2, v2, s92
	v_and_b32_e32 v0, 0x70, v0
	v_add3_u32 v0, s0, v2, v0
	s_max_u32 s0, s9, 5
	s_waitcnt vmcnt(0)
	ds_write_b128 v0, v[108:111] offset:27648
	s_add_i32 s28, s0, -4
	v_mov_b32_e32 v0, v167
	s_lshl_b64 s[0:1], s[28:29], 18
	s_add_u32 s0, s44, s0
	v_ashrrev_i32_e32 v4, 3, v0
	v_ashrrev_i32_e32 v5, 31, v4
	s_addc_u32 s1, s45, s1
	v_lshlrev_b64 v[4:5], 12, v[4:5]
	v_lshlrev_b32_e32 v0, 4, v0
	v_lshl_add_u64 v[4:5], s[0:1], 0, v[4:5]
	v_and_b32_e32 v0, 0x70, v0
	v_lshl_add_u64 v[4:5], v[4:5], 0, v[0:1]
	s_lshl_b32 s28, s28, 6
	v_mov_b32_e32 v0, v167
	global_load_dwordx4 v[96:99], v[4:5], off offset:2048
	s_lshl_b64 s[0:1], s[28:29], 1
	s_add_u32 s0, s46, s0
	v_ashrrev_i32_e32 v4, 3, v0
	v_ashrrev_i32_e32 v5, 31, v4
	s_addc_u32 s1, s47, s1
	v_lshlrev_b64 v[4:5], 13, v[4:5]
	v_lshlrev_b32_e32 v0, 4, v0
	v_lshl_add_u64 v[4:5], s[0:1], 0, v[4:5]
	v_and_b32_e32 v0, 0x70, v0
	v_lshl_add_u64 v[4:5], v[4:5], 0, v[0:1]
	v_mov_b32_e32 v0, v167
	v_sub_u32_e64 v2, s9, 5 clamp
	global_load_dwordx4 v[100:103], v[4:5], off
	v_lshlrev_b64 v[4:5], 18, v[2:3]
	v_ashrrev_i32_e32 v6, 3, v0
	v_ashrrev_i32_e32 v7, 31, v6
	v_lshl_add_u64 v[4:5], s[44:45], 0, v[4:5]
	v_lshlrev_b64 v[6:7], 12, v[6:7]
	v_lshlrev_b32_e32 v0, 4, v0
	v_lshl_add_u64 v[4:5], v[4:5], 0, v[6:7]
	v_and_b32_e32 v0, 0x70, v0
	v_lshl_add_u64 v[4:5], v[4:5], 0, v[0:1]
	v_lshlrev_b32_e32 v0, 6, v2
	v_lshlrev_b64 v[2:3], 1, v[0:1]
	v_mov_b32_e32 v0, v167
	global_load_dwordx4 v[104:107], v[4:5], off offset:2048
	v_lshl_add_u64 v[2:3], s[46:47], 0, v[2:3]
	v_ashrrev_i32_e32 v4, 3, v0
	v_ashrrev_i32_e32 v5, 31, v4
	v_lshlrev_b64 v[4:5], 13, v[4:5]
	v_lshlrev_b32_e32 v0, 4, v0
	v_lshl_add_u64 v[2:3], v[2:3], 0, v[4:5]
	v_and_b32_e32 v0, 0x70, v0
	v_lshl_add_u64 v[2:3], v[2:3], 0, v[0:1]
	global_load_dwordx4 v[108:111], v[2:3], off
	s_sub_i32 s0, s10, 63
	v_cmp_lt_i32_e32 vcc, s0, v119
	s_and_saveexec_b64 s[48:49], vcc
	s_cbranch_execz .LBB0_488
	v_cmp_lt_f32_e32 vcc, 0, v117
	s_cbranch_vccz .LBB0_488
	v_lshl_add_u32 v0, v121, 1, s14
	ds_read_b128 v[2:5], v0
	ds_read_b128 v[6:9], v0 offset:32
	ds_read_b128 v[10:13], v0 offset:64
	ds_read_b128 v[122:125], v0 offset:96
	ds_read_b128 v[64:67], v0 offset:4608
	ds_read_b128 v[126:129], v0 offset:4640
	ds_read_b128 v[130:133], v0 offset:4672
	ds_read_b128 v[134:137], v0 offset:4704
	s_setprio 1
	s_waitcnt lgkmcnt(7)
	v_mfma_f32_32x32x16_bf16 v[48:63], v[2:5], v[80:83], 0
	s_waitcnt lgkmcnt(3)
	v_mfma_f32_32x32x16_bf16 v[64:79], v[64:67], v[80:83], 0
	v_mfma_f32_32x32x16_bf16 v[48:63], v[6:9], v[84:87], v[48:63]
	s_waitcnt lgkmcnt(2)
	v_mfma_f32_32x32x16_bf16 v[64:79], v[126:129], v[84:87], v[64:79]
	v_mfma_f32_32x32x16_bf16 v[48:63], v[10:13], v[88:91], v[48:63]
	s_waitcnt lgkmcnt(1)
	v_mfma_f32_32x32x16_bf16 v[64:79], v[130:133], v[88:91], v[64:79]
	v_mfma_f32_32x32x16_bf16 v[48:63], v[122:125], v[92:95], v[48:63]
	s_waitcnt lgkmcnt(0)
	v_mfma_f32_32x32x16_bf16 v[64:79], v[134:137], v[92:95], v[64:79]
	s_setprio 0
	s_nop 10
	v_exp_f32_e32 v0, v64
	v_exp_f32_e32 v2, v65
	v_add_u32_e32 v13, s10, v113
	v_subrev_u32_e32 v3, 31, v13
	v_add_f32_e32 v0, 1.0, v0
	v_rcp_f32_e32 v0, v0
	v_cmp_lt_u32_e32 vcc, s10, v118
	s_cmp_eq_u64 vcc, exec
	s_cbranch_scc0 .Lsb_slow1
	v_add_f32_e32 v2, 1.0, v2
	v_mov_b32_e32 v3, v0
	v_sub_f32_e32 v0, 1.0, v0
	v_rcp_f32_e32 v64, v2
	v_exp_f32_e32 v4, v66
	v_sub_f32_e32 v65, 1.0, v64
	v_add_f32_e32 v2, 1.0, v4
	v_rcp_f32_e32 v66, v2
	v_exp_f32_e32 v4, v67
	v_sub_f32_e32 v67, 1.0, v66
	v_add_f32_e32 v2, 1.0, v4
	v_rcp_f32_e32 v2, v2
	v_exp_f32_e32 v4, v68
	v_mov_b32_e32 v68, v2
	v_sub_f32_e32 v122, 1.0, v2
	v_add_f32_e32 v2, 1.0, v4
	v_rcp_f32_e32 v5, v2
	v_exp_f32_e32 v4, v69
	v_sub_f32_e32 v12, 1.0, v5
	v_add_f32_e32 v2, 1.0, v4
	v_rcp_f32_e32 v14, v2
	v_exp_f32_e32 v4, v70
	v_sub_f32_e32 v15, 1.0, v14
	v_add_f32_e32 v2, 1.0, v4
	v_rcp_f32_e32 v69, v2
	v_exp_f32_e32 v4, v71
	v_sub_f32_e32 v70, 1.0, v69
	v_add_f32_e32 v2, 1.0, v4
	v_rcp_f32_e32 v71, v2
	v_exp_f32_e32 v4, v72
	v_sub_f32_e32 v72, 1.0, v71
	v_add_f32_e32 v2, 1.0, v4
	v_rcp_f32_e32 v6, v2
	v_exp_f32_e32 v4, v73
	v_sub_f32_e32 v73, 1.0, v6
	v_add_f32_e32 v2, 1.0, v4
	v_rcp_f32_e32 v8, v2
	v_exp_f32_e32 v4, v74
	v_sub_f32_e32 v74, 1.0, v8
	v_add_f32_e32 v2, 1.0, v4
	v_rcp_f32_e32 v2, v2
	v_exp_f32_e32 v4, v75
	v_mov_b32_e32 v75, v2
	v_sub_f32_e32 v123, 1.0, v2
	v_add_f32_e32 v2, 1.0, v4
	v_rcp_f32_e32 v2, v2
	v_exp_f32_e32 v4, v76
	v_mov_b32_e32 v76, v2
	v_sub_f32_e32 v124, 1.0, v2
	v_add_f32_e32 v2, 1.0, v4
	v_rcp_f32_e32 v7, v2
	v_exp_f32_e32 v4, v77
	v_sub_f32_e32 v77, 1.0, v7
	v_add_f32_e32 v2, 1.0, v4
	v_rcp_f32_e32 v2, v2
	v_exp_f32_e32 v4, v78
	v_mov_b32_e32 v78, v2
	v_sub_f32_e32 v125, 1.0, v2
	v_add_f32_e32 v2, 1.0, v4
	v_rcp_f32_e32 v2, v2
	v_exp_f32_e32 v4, v79
; DI float half_other(float x, int hh) { float a, b; half_swap(x, a, b); return hh ? a : b; }
; DI void sb_item(const bf16_t* __restrict__ P, const bf16_t* __restrict__ VT, bf16_t* __restrict__ Y, int item, char* lds) {
;     ...
;         float G[4], Go[4];
; #pragma unroll
;         for (int j = 0; j < 4; ++j) { G[j] = (st[4 * j] * st[4 * j + 1]) * (st[4 * j + 2] * st[4 * j + 3]); Go[j] = half_other(G[j], hh); }
;         float T = carry;
; #pragma unroll
;         for (int j = 3; j >= 0; --j) {
;           float run = hh ? T : T * Go[j];
; #pragma unroll
;           for (int e = 3; e >= 0; --e) {
;             const int idx = 4 * j + e;
;             S[kt2][idx] *= run;
;             run *= st[idx];
;           }
;           T *= G[j] * Go[j];
;         }
;         carry = T;
;       }
;       pv_tile(kcur + TS, S, O, l32, hh);
	v_mov_b32_e32 v79, v2
	v_sub_f32_e32 v126, 1.0, v2
	v_add_f32_e32 v2, 1.0, v4
	v_rcp_f32_e32 v127, v2
	v_mul_f32_e32 v7, v7, v78
	v_sub_f32_e32 v128, 1.0, v127
	v_mul_f32_e32 v2, v3, v64
	v_mul_f32_e32 v3, v66, v68
	v_mul_f32_e32 v4, v2, v3
	v_mov_b32_e32 v2, v4
	v_mov_b32_e32 v3, v4
	s_nop 1
	v_permlane32_swap_b32_e32 v2, v3
	v_cndmask_b32_e64 v2, v2, v3, s[40:41]
	v_mul_f32_e32 v3, v5, v14
	v_mul_f32_e32 v5, v69, v71
	v_mul_f32_e32 v3, v3, v5
	v_mov_b32_e32 v5, v3
	v_mov_b32_e32 v9, v3
	s_nop 1
	v_permlane32_swap_b32_e32 v5, v9
	v_cndmask_b32_e64 v5, v5, v9, s[40:41]
	v_mul_f32_e32 v9, v79, v127
	v_pk_mul_f32 v[6:7], v[6:7], v[8:9]
	v_mul_f32_e32 v10, v75, v76
	v_mov_b32_e32 v9, v7
	v_mov_b32_e32 v11, v7
	s_nop 1
	v_permlane32_swap_b32_e32 v9, v11
	v_cndmask_b32_e64 v11, v9, v11, s[40:41]
	v_pk_mul_f32 v[6:7], v[6:7], v[10:11]
	s_nop 0
	v_mov_b32_e32 v9, v6
	v_mov_b32_e32 v10, v6
	s_nop 1
	v_permlane32_swap_b32_e32 v9, v10
	v_cndmask_b32_e64 v116, v9, v10, s[40:41]
	v_mul_f32_e32 v9, v117, v11
	v_cndmask_b32_e64 v9, v117, v9, s[40:41]
	v_mul_f32_e32 v128, v128, v9
	v_mul_f32_e32 v9, v127, v9
	v_mul_f32_e32 v126, v126, v9
	v_mul_f32_e32 v9, v79, v9
	v_mul_f32_e32 v79, v125, v9
	v_mul_f32_e32 v9, v78, v9
	v_pk_mul_f32 v[6:7], v[6:7], v[116:117]
	v_mul_f32_e32 v77, v77, v9
	v_mul_f32_e32 v9, v7, v116
	v_pk_mul_f32 v[10:11], v[6:7], v[6:7] op_sel:[0,1] op_sel_hi:[1,0]
	v_cndmask_b32_e64 v9, v7, v9, s[40:41]
	v_mul_f32_e32 v6, v10, v5
	v_exp_f32_e32 v7, v48
	v_cndmask_b32_e64 v6, v10, v6, s[40:41]
	v_mul_f32_e32 v72, v72, v6
	v_mul_f32_e32 v6, v71, v6
	v_mul_f32_e32 v70, v70, v6
	v_mul_f32_e32 v6, v69, v6
	v_mul_f32_e32 v69, v15, v6
	v_mul_f32_e32 v6, v14, v6
	v_mul_f32_e32 v14, v3, v5
	v_add_f32_e32 v3, 1.0, v7
	v_rcp_f32_e32 v3, v3
	v_mul_f32_e32 v78, v124, v9
	v_mul_f32_e32 v9, v76, v9
	v_exp_f32_e32 v5, v49
	v_mul_f32_e32 v76, v123, v9
	v_mul_f32_e32 v9, v75, v9
	v_mul_f32_e32 v8, v8, v9
	v_mul_f32_e32 v73, v73, v8
	v_mov_b32_e32 v8, v3
	v_sub_f32_e32 v75, 1.0, v3
	v_add_f32_e32 v3, 1.0, v5
	v_rcp_f32_e32 v3, v3
	v_exp_f32_e32 v5, v50
	v_mul_f32_e32 v71, v12, v6
	v_mov_b32_e32 v6, v3
	v_sub_f32_e32 v116, 1.0, v3
	v_add_f32_e32 v3, 1.0, v5
	v_rcp_f32_e32 v12, v3
	v_exp_f32_e32 v5, v51
	v_sub_f32_e32 v117, 1.0, v12
	v_add_f32_e32 v3, 1.0, v5
	v_rcp_f32_e32 v48, v3
	v_exp_f32_e32 v5, v52
	v_sub_f32_e32 v123, 1.0, v48
	v_add_f32_e32 v3, 1.0, v5
	v_rcp_f32_e32 v7, v3
	v_exp_f32_e32 v5, v53
	v_sub_f32_e32 v124, 1.0, v7
	v_add_f32_e32 v3, 1.0, v5
	v_rcp_f32_e32 v3, v3
	v_exp_f32_e32 v5, v54
	v_mov_b32_e32 v54, v3
	v_sub_f32_e32 v125, 1.0, v3
	v_add_f32_e32 v3, 1.0, v5
	v_rcp_f32_e32 v3, v3
	v_exp_f32_e32 v5, v55
	v_mov_b32_e32 v55, v3
	v_sub_f32_e32 v127, 1.0, v3
	v_add_f32_e32 v3, 1.0, v5
	v_rcp_f32_e32 v3, v3
	v_exp_f32_e32 v5, v56
	v_mov_b32_e32 v56, v3
	v_sub_f32_e32 v129, 1.0, v3
	v_add_f32_e32 v3, 1.0, v5
	v_rcp_f32_e32 v49, v3
	v_exp_f32_e32 v5, v57
	v_sub_f32_e32 v52, 1.0, v49
	v_add_f32_e32 v3, 1.0, v5
	v_rcp_f32_e32 v53, v3
	v_exp_f32_e32 v5, v58
	v_sub_f32_e32 v57, 1.0, v53
	v_add_f32_e32 v3, 1.0, v5
	v_rcp_f32_e32 v58, v3
	v_exp_f32_e32 v5, v59
	v_sub_f32_e32 v59, 1.0, v58
	v_add_f32_e32 v3, 1.0, v5
	v_rcp_f32_e32 v3, v3
	v_exp_f32_e32 v5, v60
	v_mov_b32_e32 v60, v3
	v_sub_f32_e32 v130, 1.0, v3
	v_add_f32_e32 v3, 1.0, v5
	v_rcp_f32_e32 v5, v3
	v_mul_f32_e32 v74, v74, v9
	v_exp_f32_e32 v9, v61
	v_exp_f32_e32 v11, v62
	v_sub_f32_e32 v61, 1.0, v5
	v_add_f32_e32 v3, 1.0, v9
	v_rcp_f32_e32 v3, v3
	v_mul_f32_e32 v7, v7, v54
	v_sub_f32_e32 v62, 1.0, v3
	v_add_f32_e32 v9, 1.0, v11
	v_rcp_f32_e32 v15, v9
	v_exp_f32_e32 v11, v63
	v_sub_f32_e32 v63, 1.0, v15
	v_add_f32_e32 v9, 1.0, v11
	v_rcp_f32_e32 v11, v9
	s_nop 0
	v_sub_f32_e32 v13, 1.0, v11
	v_mul_f32_e32 v9, v55, v56
	v_mul_f32_e32 v9, v7, v9
	v_mov_b32_e32 v7, v9
	v_mov_b32_e32 v50, v9
	s_nop 1
	v_permlane32_swap_b32_e32 v7, v50
	v_cndmask_b32_e64 v7, v7, v50, s[40:41]
	v_mul_f32_e32 v49, v49, v53
	v_mul_f32_e32 v50, v58, v60
	v_mul_f32_e32 v131, v49, v50
	v_mov_b32_e32 v49, v131
	v_mov_b32_e32 v50, v131
	s_nop 1
	v_permlane32_swap_b32_e32 v49, v50
	v_cndmask_b32_e64 v132, v49, v50, s[40:41]
	v_pk_mul_f32 v[50:51], v[14:15], v[10:11]
	v_pk_mul_f32 v[4:5], v[4:5], v[2:3]
	v_mul_f32_e32 v10, v50, v2
	v_cndmask_b32_e64 v10, v50, v10, s[40:41]
	v_mul_f32_e32 v122, v122, v10
	v_mul_f32_e32 v10, v68, v10
	v_mul_f32_e32 v67, v67, v10
	v_mul_f32_e32 v10, v66, v10
	v_mul_f32_e32 v65, v65, v10
	v_mul_f32_e32 v10, v64, v10
	v_pk_mul_f32 v[4:5], v[4:5], v[50:51]
	v_mul_f32_e32 v0, v0, v10
	v_mov_b32_e32 v2, v5
	v_mov_b32_e32 v10, v5
	s_nop 1
	v_permlane32_swap_b32_e32 v2, v10
	v_cndmask_b32_e64 v2, v2, v10, s[40:41]
	v_mul_f32_e32 v10, v4, v2
	v_mul_f32_e32 v2, v5, v2
	v_mul_f32_e32 v49, v4, v2
	v_mul_f32_e32 v2, v49, v132
	v_cndmask_b32_e64 v10, v4, v10, s[40:41]
	v_cndmask_b32_e64 v2, v49, v2, s[40:41]
	v_mul_f32_e32 v64, v13, v10
	v_mul_f32_e32 v10, v11, v10
	v_mul_f32_e32 v66, v130, v2
	v_mul_f32_e32 v2, v60, v2
	v_mul_f32_e32 v63, v63, v10
	v_mul_f32_e32 v10, v15, v10
	v_mul_f32_e32 v59, v59, v2
	v_mul_f32_e32 v2, v58, v2
	v_mul_f32_e32 v3, v3, v10
	v_mul_f32_e32 v57, v57, v2
	v_mul_f32_e32 v2, v53, v2
	v_mul_f32_e32 v13, v131, v132
	v_mul_f32_e32 v61, v61, v3
	v_mul_f32_e32 v58, v52, v2
	v_pk_mul_f32 v[2:3], v[12:13], v[48:49]
	v_pk_mul_f32 v[4:5], v[8:9], v[6:7]
	v_mul_f32_e32 v62, v62, v10
	v_pk_mul_f32 v[52:53], v[4:5], v[2:3]
	s_nop 0
	v_mov_b32_e32 v2, v52
	v_mov_b32_e32 v4, v52
	s_nop 1
	v_permlane32_swap_b32_e32 v2, v4
	v_cndmask_b32_e64 v60, v2, v4, s[40:41]
	v_mul_f32_e32 v2, v3, v7
	v_cndmask_b32_e64 v2, v3, v2, s[40:41]
	v_mul_f32_e32 v7, v129, v2
	v_mul_f32_e32 v2, v56, v2
	v_mul_f32_e32 v56, v127, v2
	v_mul_f32_e32 v2, v55, v2
	v_mul_f32_e32 v55, v125, v2
	v_mul_f32_e32 v2, v54, v2
	v_mul_f32_e32 v54, v124, v2
	v_mul_f32_e32 v2, v53, v60
	v_cndmask_b32_e64 v2, v53, v2, s[40:41]
	v_mul_f32_e32 v68, v123, v2
	v_mul_f32_e32 v2, v48, v2
	v_mul_f32_e32 v123, v117, v2
	v_mul_f32_e32 v117, v12, v2
	v_lshlrev_b32_e32 v2, 1, v113
	v_lshlrev_b32_e32 v3, 1, v120
	v_add3_u32 v12, s14, v2, v3
	v_add_u32_e32 v124, 0x2000, v12
	v_add_u32_e32 v125, 0x3000, v12
	ds_read2_b64 v[2:5], v124 offset0:128 offset1:130
	ds_read2_b64 v[8:11], v124 offset0:132 offset1:134
	ds_read2_b64 v[12:15], v125 offset0:192 offset1:194
	ds_read2_b64 v[48:51], v125 offset0:196 offset1:198
	v_mul_f32_e32 v52, v52, v60
	v_mul_f32_e32 v116, v116, v117
	v_mul_f32_e32 v6, v6, v117
	v_mul_f32_e32 v117, v52, v53
	v_mul_f32_e32 v6, v75, v6
	s_branch .Lsb_join1
; DI int crow(int reg, int hh) { return (reg & 3) + 8 * (reg >> 2) + 4 * hh; }
; DI float ex2(float x) { return __builtin_amdgcn_exp2f(x); }
; DI void sb_item(const bf16_t* __restrict__ P, const bf16_t* __restrict__ VT, bf16_t* __restrict__ Y, int item, char* lds) {
;     ...
; #pragma unroll
;         for (int e = 0; e < 16; ++e) {
;           const float ez = ex2(S[kt2][e]);
;           const float r = __builtin_amdgcn_rcpf(1.f + ez);
;           const bool vis = full || (kb * 64 + kt2 * 32 + crow(e, hh) < qpos);
;           st[e] = vis ? r : 1.f;
;           S[kt2][e] = vis ? 1.f - r : 0.f;
;         }
.Lsb_slow1:
	v_cmp_lt_i32_e64 s[0:1], v3, v112
	s_or_b64 s[0:1], vcc, s[0:1]
	v_add_f32_e32 v2, 1.0, v2
	v_cndmask_b32_e64 v3, 1.0, v0, s[0:1]
	v_sub_f32_e32 v0, 1.0, v0
	v_rcp_f32_e32 v2, v2
	v_subrev_u32_e32 v4, 30, v13
	v_cndmask_b32_e64 v0, 0, v0, s[0:1]
	v_cmp_lt_i32_e64 s[0:1], v4, v112
	v_exp_f32_e32 v4, v66
	s_or_b64 s[0:1], vcc, s[0:1]
	v_cndmask_b32_e64 v64, 1.0, v2, s[0:1]
	v_sub_f32_e32 v2, 1.0, v2
	v_cndmask_b32_e64 v65, 0, v2, s[0:1]
	v_add_f32_e32 v2, 1.0, v4
	v_rcp_f32_e32 v2, v2
	v_subrev_u32_e32 v4, 29, v13
	v_cmp_lt_i32_e64 s[0:1], v4, v112
	v_exp_f32_e32 v4, v67
	s_or_b64 s[0:1], vcc, s[0:1]
	v_cndmask_b32_e64 v66, 1.0, v2, s[0:1]
	v_sub_f32_e32 v2, 1.0, v2
	v_cndmask_b32_e64 v67, 0, v2, s[0:1]
	v_add_f32_e32 v2, 1.0, v4
	v_rcp_f32_e32 v2, v2
	v_subrev_u32_e32 v4, 28, v13
	v_cmp_lt_i32_e64 s[0:1], v4, v112
	v_exp_f32_e32 v4, v68
	s_or_b64 s[0:1], vcc, s[0:1]
	v_cndmask_b32_e64 v68, 1.0, v2, s[0:1]
	v_sub_f32_e32 v2, 1.0, v2
	v_cndmask_b32_e64 v122, 0, v2, s[0:1]
	v_add_f32_e32 v2, 1.0, v4
	v_rcp_f32_e32 v2, v2
	v_subrev_u32_e32 v4, 23, v13
	v_cmp_lt_i32_e64 s[0:1], v4, v112
	v_exp_f32_e32 v4, v69
	s_or_b64 s[0:1], vcc, s[0:1]
	v_cndmask_b32_e64 v5, 1.0, v2, s[0:1]
	v_sub_f32_e32 v2, 1.0, v2
	v_cndmask_b32_e64 v12, 0, v2, s[0:1]
	v_add_f32_e32 v2, 1.0, v4
	v_rcp_f32_e32 v2, v2
	v_subrev_u32_e32 v4, 22, v13
	v_cmp_lt_i32_e64 s[0:1], v4, v112
	v_exp_f32_e32 v4, v70
	s_or_b64 s[0:1], vcc, s[0:1]
	v_cndmask_b32_e64 v14, 1.0, v2, s[0:1]
	v_sub_f32_e32 v2, 1.0, v2
	v_cndmask_b32_e64 v15, 0, v2, s[0:1]
	v_add_f32_e32 v2, 1.0, v4
	v_rcp_f32_e32 v2, v2
	v_subrev_u32_e32 v4, 21, v13
	v_cmp_lt_i32_e64 s[0:1], v4, v112
	v_exp_f32_e32 v4, v71
	s_or_b64 s[0:1], vcc, s[0:1]
	v_cndmask_b32_e64 v69, 1.0, v2, s[0:1]
	v_sub_f32_e32 v2, 1.0, v2
	v_cndmask_b32_e64 v70, 0, v2, s[0:1]
	v_add_f32_e32 v2, 1.0, v4
	v_rcp_f32_e32 v2, v2
	v_subrev_u32_e32 v4, 20, v13
	v_cmp_lt_i32_e64 s[0:1], v4, v112
	v_exp_f32_e32 v4, v72
	s_or_b64 s[0:1], vcc, s[0:1]
	v_cndmask_b32_e64 v71, 1.0, v2, s[0:1]
	v_sub_f32_e32 v2, 1.0, v2
	v_cndmask_b32_e64 v72, 0, v2, s[0:1]
	v_add_f32_e32 v2, 1.0, v4
	v_rcp_f32_e32 v2, v2
	v_add_u32_e32 v4, -15, v13
	v_cmp_lt_i32_e64 s[0:1], v4, v112
	v_exp_f32_e32 v4, v73
	s_or_b64 s[0:1], vcc, s[0:1]
	v_cndmask_b32_e64 v6, 1.0, v2, s[0:1]
	v_sub_f32_e32 v2, 1.0, v2
	v_cndmask_b32_e64 v73, 0, v2, s[0:1]
	v_add_f32_e32 v2, 1.0, v4
	v_rcp_f32_e32 v2, v2
	v_add_u32_e32 v4, -14, v13
	v_cmp_lt_i32_e64 s[0:1], v4, v112
	v_exp_f32_e32 v4, v74
	s_or_b64 s[0:1], vcc, s[0:1]
	v_cndmask_b32_e64 v8, 1.0, v2, s[0:1]
	v_sub_f32_e32 v2, 1.0, v2
	v_cndmask_b32_e64 v74, 0, v2, s[0:1]
	v_add_f32_e32 v2, 1.0, v4
	v_rcp_f32_e32 v2, v2
	v_add_u32_e32 v4, -13, v13
	v_cmp_lt_i32_e64 s[0:1], v4, v112
	v_exp_f32_e32 v4, v75
	s_or_b64 s[0:1], vcc, s[0:1]
	v_cndmask_b32_e64 v75, 1.0, v2, s[0:1]
	v_sub_f32_e32 v2, 1.0, v2
	v_cndmask_b32_e64 v123, 0, v2, s[0:1]
	v_add_f32_e32 v2, 1.0, v4
	v_rcp_f32_e32 v2, v2
	v_add_u32_e32 v4, -12, v13
	v_cmp_lt_i32_e64 s[0:1], v4, v112
	v_exp_f32_e32 v4, v76
	s_or_b64 s[0:1], vcc, s[0:1]
	v_cndmask_b32_e64 v76, 1.0, v2, s[0:1]
	v_sub_f32_e32 v2, 1.0, v2
	v_cndmask_b32_e64 v124, 0, v2, s[0:1]
	v_add_f32_e32 v2, 1.0, v4
	v_rcp_f32_e32 v2, v2
	v_add_u32_e32 v4, -7, v13
	v_cmp_lt_i32_e64 s[0:1], v4, v112
	v_exp_f32_e32 v4, v77
	s_or_b64 s[0:1], vcc, s[0:1]
	v_cndmask_b32_e64 v7, 1.0, v2, s[0:1]
	v_sub_f32_e32 v2, 1.0, v2
	v_cndmask_b32_e64 v77, 0, v2, s[0:1]
	v_add_f32_e32 v2, 1.0, v4
	v_rcp_f32_e32 v2, v2
	v_add_u32_e32 v4, -6, v13
	v_cmp_lt_i32_e64 s[0:1], v4, v112
	v_exp_f32_e32 v4, v78
	s_or_b64 s[0:1], vcc, s[0:1]
	v_cndmask_b32_e64 v78, 1.0, v2, s[0:1]
	v_sub_f32_e32 v2, 1.0, v2
	v_cndmask_b32_e64 v125, 0, v2, s[0:1]
	v_add_f32_e32 v2, 1.0, v4
	v_rcp_f32_e32 v2, v2
	v_add_u32_e32 v4, -5, v13
	v_cmp_lt_i32_e64 s[0:1], v4, v112
	v_exp_f32_e32 v4, v79
	s_or_b64 s[0:1], vcc, s[0:1]
	v_cndmask_b32_e64 v79, 1.0, v2, s[0:1]
	v_sub_f32_e32 v2, 1.0, v2
	v_cndmask_b32_e64 v126, 0, v2, s[0:1]
	v_add_f32_e32 v2, 1.0, v4
	v_rcp_f32_e32 v2, v2
	v_add_u32_e32 v4, -4, v13
	v_cmp_lt_i32_e64 s[0:1], v4, v112
	s_or_b64 s[0:1], vcc, s[0:1]
	v_mul_f32_e32 v7, v7, v78
	v_cndmask_b32_e64 v127, 1.0, v2, s[0:1]
	v_sub_f32_e32 v2, 1.0, v2
	v_cndmask_b32_e64 v128, 0, v2, s[0:1]
	v_mul_f32_e32 v2, v3, v64
	v_mul_f32_e32 v3, v66, v68
	v_mul_f32_e32 v4, v2, v3
	v_mov_b32_e32 v2, v4
	v_mov_b32_e32 v3, v4
	s_nop 1
	v_permlane32_swap_b32_e32 v2, v3
	v_cndmask_b32_e64 v2, v2, v3, s[40:41]
	v_mul_f32_e32 v3, v5, v14
	v_mul_f32_e32 v5, v69, v71
	v_mul_f32_e32 v3, v3, v5
	v_mov_b32_e32 v5, v3
	v_mov_b32_e32 v9, v3
	s_nop 1
	v_permlane32_swap_b32_e32 v5, v9
	v_cndmask_b32_e64 v5, v5, v9, s[40:41]
	v_mul_f32_e32 v9, v79, v127
	v_pk_mul_f32 v[6:7], v[6:7], v[8:9]
	v_mul_f32_e32 v10, v75, v76
	v_mov_b32_e32 v9, v7
	v_mov_b32_e32 v11, v7
	s_nop 1
	v_permlane32_swap_b32_e32 v9, v11
	v_cndmask_b32_e64 v11, v9, v11, s[40:41]
	v_pk_mul_f32 v[6:7], v[6:7], v[10:11]
	s_nop 0
	v_mov_b32_e32 v9, v6
	v_mov_b32_e32 v10, v6
	s_nop 1
	v_permlane32_swap_b32_e32 v9, v10
	v_cndmask_b32_e64 v116, v9, v10, s[40:41]
	v_mul_f32_e32 v9, v117, v11
	v_cndmask_b32_e64 v9, v117, v9, s[40:41]
	v_mul_f32_e32 v128, v128, v9
	v_mul_f32_e32 v9, v127, v9
	v_mul_f32_e32 v126, v126, v9
	v_mul_f32_e32 v9, v79, v9
	v_mul_f32_e32 v79, v125, v9
	v_mul_f32_e32 v9, v78, v9
	v_pk_mul_f32 v[6:7], v[6:7], v[116:117]
	v_mul_f32_e32 v77, v77, v9
	v_mul_f32_e32 v9, v7, v116
	v_pk_mul_f32 v[10:11], v[6:7], v[6:7] op_sel:[0,1] op_sel_hi:[1,0]
	v_cndmask_b32_e64 v9, v7, v9, s[40:41]
	v_mul_f32_e32 v6, v10, v5
	v_exp_f32_e32 v7, v48
	v_cndmask_b32_e64 v6, v10, v6, s[40:41]
	v_mul_f32_e32 v72, v72, v6
; DI float half_other(float x, int hh) { float a, b; half_swap(x, a, b); return hh ? a : b; }
; DI int crow(int reg, int hh) { return (reg & 3) + 8 * (reg >> 2) + 4 * hh; }
; DI float ex2(float x) { return __builtin_amdgcn_exp2f(x); }
; DI void sb_item(const bf16_t* __restrict__ P, const bf16_t* __restrict__ VT, bf16_t* __restrict__ Y, int item, char* lds) {
;     ...
;         float st[16];
; #pragma unroll
;         for (int e = 0; e < 16; ++e) {
;           const float ez = ex2(S[kt2][e]);
;           const float r = __builtin_amdgcn_rcpf(1.f + ez);
;           const bool vis = full || (kb * 64 + kt2 * 32 + crow(e, hh) < qpos);
;           st[e] = vis ? r : 1.f;
;           S[kt2][e] = vis ? 1.f - r : 0.f;
;         }
;         float G[4], Go[4];
; #pragma unroll
;         for (int j = 0; j < 4; ++j) { G[j] = (st[4 * j] * st[4 * j + 1]) * (st[4 * j + 2] * st[4 * j + 3]); Go[j] = half_other(G[j], hh); }
;         float T = carry;
; #pragma unroll
;         for (int j = 3; j >= 0; --j) {
;           float run = hh ? T : T * Go[j];
; #pragma unroll
;           for (int e = 3; e >= 0; --e) {
;             const int idx = 4 * j + e;
;             S[kt2][idx] *= run;
;             run *= st[idx];
;           }
;           T *= G[j] * Go[j];
;         }
;         carry = T;
	v_mul_f32_e32 v6, v71, v6
	v_mul_f32_e32 v70, v70, v6
	v_mul_f32_e32 v6, v69, v6
	v_mul_f32_e32 v69, v15, v6
	v_mul_f32_e32 v6, v14, v6
	v_mul_f32_e32 v14, v3, v5
	v_add_f32_e32 v3, 1.0, v7
	v_rcp_f32_e32 v3, v3
	v_subrev_u32_e32 v5, 63, v13
	v_mul_f32_e32 v78, v124, v9
	v_mul_f32_e32 v9, v76, v9
	v_cmp_lt_i32_e64 s[0:1], v5, v112
	v_exp_f32_e32 v5, v49
	v_mul_f32_e32 v76, v123, v9
	v_mul_f32_e32 v9, v75, v9
	v_mul_f32_e32 v8, v8, v9
	s_or_b64 s[0:1], vcc, s[0:1]
	v_mul_f32_e32 v73, v73, v8
	v_cndmask_b32_e64 v8, 1.0, v3, s[0:1]
	v_sub_f32_e32 v3, 1.0, v3
	v_cndmask_b32_e64 v75, 0, v3, s[0:1]
	v_add_f32_e32 v3, 1.0, v5
	v_rcp_f32_e32 v3, v3
	v_subrev_u32_e32 v5, 62, v13
	v_cmp_lt_i32_e64 s[0:1], v5, v112
	v_exp_f32_e32 v5, v50
	s_or_b64 s[0:1], vcc, s[0:1]
	v_mul_f32_e32 v71, v12, v6
	v_cndmask_b32_e64 v6, 1.0, v3, s[0:1]
	v_sub_f32_e32 v3, 1.0, v3
	v_cndmask_b32_e64 v116, 0, v3, s[0:1]
	v_add_f32_e32 v3, 1.0, v5
	v_rcp_f32_e32 v3, v3
	v_subrev_u32_e32 v5, 61, v13
	v_cmp_lt_i32_e64 s[0:1], v5, v112
	v_exp_f32_e32 v5, v51
	s_or_b64 s[0:1], vcc, s[0:1]
	v_cndmask_b32_e64 v12, 1.0, v3, s[0:1]
	v_sub_f32_e32 v3, 1.0, v3
	v_cndmask_b32_e64 v117, 0, v3, s[0:1]
	v_add_f32_e32 v3, 1.0, v5
	v_rcp_f32_e32 v3, v3
	v_subrev_u32_e32 v5, 60, v13
	v_cmp_lt_i32_e64 s[0:1], v5, v112
	v_exp_f32_e32 v5, v52
	s_or_b64 s[0:1], vcc, s[0:1]
	v_cndmask_b32_e64 v48, 1.0, v3, s[0:1]
	v_sub_f32_e32 v3, 1.0, v3
	v_cndmask_b32_e64 v123, 0, v3, s[0:1]
	v_add_f32_e32 v3, 1.0, v5
	v_rcp_f32_e32 v3, v3
	v_subrev_u32_e32 v5, 55, v13
	v_cmp_lt_i32_e64 s[0:1], v5, v112
	v_exp_f32_e32 v5, v53
	s_or_b64 s[0:1], vcc, s[0:1]
	v_cndmask_b32_e64 v7, 1.0, v3, s[0:1]
	v_sub_f32_e32 v3, 1.0, v3
	v_cndmask_b32_e64 v124, 0, v3, s[0:1]
	v_add_f32_e32 v3, 1.0, v5
	v_rcp_f32_e32 v3, v3
	v_subrev_u32_e32 v5, 54, v13
	v_cmp_lt_i32_e64 s[0:1], v5, v112
	v_exp_f32_e32 v5, v54
	s_or_b64 s[0:1], vcc, s[0:1]
	v_cndmask_b32_e64 v54, 1.0, v3, s[0:1]
	v_sub_f32_e32 v3, 1.0, v3
	v_cndmask_b32_e64 v125, 0, v3, s[0:1]
	v_add_f32_e32 v3, 1.0, v5
	v_rcp_f32_e32 v3, v3
	v_subrev_u32_e32 v5, 53, v13
	v_cmp_lt_i32_e64 s[0:1], v5, v112
	v_exp_f32_e32 v5, v55
	s_or_b64 s[0:1], vcc, s[0:1]
	v_cndmask_b32_e64 v55, 1.0, v3, s[0:1]
	v_sub_f32_e32 v3, 1.0, v3
	v_cndmask_b32_e64 v127, 0, v3, s[0:1]
	v_add_f32_e32 v3, 1.0, v5
	v_rcp_f32_e32 v3, v3
	v_subrev_u32_e32 v5, 52, v13
	v_cmp_lt_i32_e64 s[0:1], v5, v112
	v_exp_f32_e32 v5, v56
	s_or_b64 s[0:1], vcc, s[0:1]
	v_cndmask_b32_e64 v56, 1.0, v3, s[0:1]
	v_sub_f32_e32 v3, 1.0, v3
	v_cndmask_b32_e64 v129, 0, v3, s[0:1]
	v_add_f32_e32 v3, 1.0, v5
	v_rcp_f32_e32 v3, v3
	v_subrev_u32_e32 v5, 47, v13
	v_cmp_lt_i32_e64 s[0:1], v5, v112
	v_exp_f32_e32 v5, v57
	s_or_b64 s[0:1], vcc, s[0:1]
	v_cndmask_b32_e64 v49, 1.0, v3, s[0:1]
	v_sub_f32_e32 v3, 1.0, v3
	v_cndmask_b32_e64 v52, 0, v3, s[0:1]
	v_add_f32_e32 v3, 1.0, v5
	v_rcp_f32_e32 v3, v3
	v_subrev_u32_e32 v5, 46, v13
	v_cmp_lt_i32_e64 s[0:1], v5, v112
	v_exp_f32_e32 v5, v58
	s_or_b64 s[0:1], vcc, s[0:1]
	v_cndmask_b32_e64 v53, 1.0, v3, s[0:1]
	v_sub_f32_e32 v3, 1.0, v3
	v_cndmask_b32_e64 v57, 0, v3, s[0:1]
	v_add_f32_e32 v3, 1.0, v5
	v_rcp_f32_e32 v3, v3
	v_subrev_u32_e32 v5, 45, v13
	v_cmp_lt_i32_e64 s[0:1], v5, v112
	v_exp_f32_e32 v5, v59
	s_or_b64 s[0:1], vcc, s[0:1]
	v_cndmask_b32_e64 v58, 1.0, v3, s[0:1]
	v_sub_f32_e32 v3, 1.0, v3
	v_cndmask_b32_e64 v59, 0, v3, s[0:1]
	v_add_f32_e32 v3, 1.0, v5
	v_rcp_f32_e32 v3, v3
	v_subrev_u32_e32 v5, 44, v13
	v_cmp_lt_i32_e64 s[0:1], v5, v112
	v_exp_f32_e32 v5, v60
	s_or_b64 s[0:1], vcc, s[0:1]
	v_cndmask_b32_e64 v60, 1.0, v3, s[0:1]
	v_sub_f32_e32 v3, 1.0, v3
	v_cndmask_b32_e64 v130, 0, v3, s[0:1]
	v_add_f32_e32 v3, 1.0, v5
	v_rcp_f32_e32 v3, v3
	v_mul_f32_e32 v74, v74, v9
	v_subrev_u32_e32 v5, 39, v13
	v_exp_f32_e32 v9, v61
	v_cmp_lt_i32_e64 s[0:1], v5, v112
	s_or_b64 s[0:1], vcc, s[0:1]
	v_exp_f32_e32 v11, v62
	v_cndmask_b32_e64 v5, 1.0, v3, s[0:1]
	v_sub_f32_e32 v3, 1.0, v3
	v_cndmask_b32_e64 v61, 0, v3, s[0:1]
	v_add_f32_e32 v3, 1.0, v9
	v_rcp_f32_e32 v9, v3
	v_subrev_u32_e32 v3, 38, v13
	v_cmp_lt_i32_e64 s[0:1], v3, v112
	s_or_b64 s[0:1], vcc, s[0:1]
	v_mul_f32_e32 v7, v7, v54
	v_cndmask_b32_e64 v3, 1.0, v9, s[0:1]
	v_sub_f32_e32 v9, 1.0, v9
	v_cndmask_b32_e64 v62, 0, v9, s[0:1]
	v_add_f32_e32 v9, 1.0, v11
	v_rcp_f32_e32 v9, v9
	v_subrev_u32_e32 v11, 37, v13
	v_cmp_lt_i32_e64 s[0:1], v11, v112
	v_exp_f32_e32 v11, v63
	s_or_b64 s[0:1], vcc, s[0:1]
	v_cndmask_b32_e64 v15, 1.0, v9, s[0:1]
	v_sub_f32_e32 v9, 1.0, v9
	v_cndmask_b32_e64 v63, 0, v9, s[0:1]
	v_add_f32_e32 v9, 1.0, v11
	v_rcp_f32_e32 v9, v9
	v_subrev_u32_e32 v11, 36, v13
	v_cmp_lt_i32_e64 s[0:1], v11, v112
	s_or_b64 vcc, vcc, s[0:1]
	v_cndmask_b32_e32 v11, 1.0, v9, vcc
	v_sub_f32_e32 v9, 1.0, v9
	v_cndmask_b32_e32 v13, 0, v9, vcc
	v_mul_f32_e32 v9, v55, v56
	v_mul_f32_e32 v9, v7, v9
	v_mov_b32_e32 v7, v9
	v_mov_b32_e32 v50, v9
	s_nop 1
	v_permlane32_swap_b32_e32 v7, v50
	v_cndmask_b32_e64 v7, v7, v50, s[40:41]
	v_mul_f32_e32 v49, v49, v53
	v_mul_f32_e32 v50, v58, v60
	v_mul_f32_e32 v131, v49, v50
	v_mov_b32_e32 v49, v131
	v_mov_b32_e32 v50, v131
	s_nop 1
	v_permlane32_swap_b32_e32 v49, v50
	v_cndmask_b32_e64 v132, v49, v50, s[40:41]
	v_pk_mul_f32 v[50:51], v[14:15], v[10:11]
	v_pk_mul_f32 v[4:5], v[4:5], v[2:3]
	v_mul_f32_e32 v10, v50, v2
	v_cndmask_b32_e64 v10, v50, v10, s[40:41]
	v_mul_f32_e32 v122, v122, v10
	v_mul_f32_e32 v10, v68, v10
	v_mul_f32_e32 v67, v67, v10
	v_mul_f32_e32 v10, v66, v10
	v_mul_f32_e32 v65, v65, v10
	v_mul_f32_e32 v10, v64, v10
	v_pk_mul_f32 v[4:5], v[4:5], v[50:51]
	v_mul_f32_e32 v0, v0, v10
	v_mov_b32_e32 v2, v5
	v_mov_b32_e32 v10, v5
	s_nop 1
	v_permlane32_swap_b32_e32 v2, v10
; #define MFMA32(a, b, c) __builtin_amdgcn_mfma_f32_32x32x16_bf16((a), (b), (c), 0, 0, 0)
; DI unsigned pack2(float a, float b) { f32x2 v = {a, b}; return __builtin_bit_cast(unsigned, __builtin_convertvector(v, hwbf16x2)); }
; DI int crow(int reg, int hh) { return (reg & 3) + 8 * (reg >> 2) + 4 * hh; }
; DI float ex2(float x) { return __builtin_amdgcn_exp2f(x); }
; DI void pv_tile(const bf16_t* VTs, const f32x16 (&Pm)[2], f32x16 (&O)[2], int l32, int hh) {
; #pragma unroll
;   for (int kt2 = 0; kt2 < 2; ++kt2) {
;     u32x2 lo[2][2], hi[2][2];
; #pragma unroll
;     for (int t = 0; t < 2; ++t)
; #pragma unroll
;       for (int dt = 0; dt < 2; ++dt) {
;         const bf16_t* vp = &VTs[(dt * 32 + l32) * LDT + kt2 * 32 + 16 * t + 4 * hh];
;         lo[t][dt] = *(const u32x2*)vp; hi[t][dt] = *(const u32x2*)(vp + 8);
;       }
;     __builtin_amdgcn_sched_barrier(0);
;     __builtin_amdgcn_s_setprio(1);
; #pragma unroll
;     for (int t = 0; t < 2; ++t) {
;       u32x4 pk;
;       pk.x = pack2(Pm[kt2][8 * t + 0], Pm[kt2][8 * t + 1]); pk.y = pack2(Pm[kt2][8 * t + 2], Pm[kt2][8 * t + 3]);
;       pk.z = pack2(Pm[kt2][8 * t + 4], Pm[kt2][8 * t + 5]); pk.w = pack2(Pm[kt2][8 * t + 6], Pm[kt2][8 * t + 7]);
;       const bf16x8 pf = __builtin_bit_cast(bf16x8, pk);
; #pragma unroll
;       for (int dt = 0; dt < 2; ++dt) {
;         u32x4 vv; vv.x = lo[t][dt].x; vv.y = lo[t][dt].y; vv.z = hi[t][dt].x; vv.w = hi[t][dt].y;
;         O[dt] = MFMA32(__builtin_bit_cast(bf16x8, vv), pf, O[dt]);
;       }
;     }
;     __builtin_amdgcn_s_setprio(0);
;   }
; DI void sb_item(const bf16_t* __restrict__ P, const bf16_t* __restrict__ VT, bf16_t* __restrict__ Y, int item, char* lds) {
;     ...
;   auto do_tile = [&](int kb, const bf16_t* kcur) {
;     const bool active = (kb * 64 < q0 + 31) && (__ballot(carry > 0.f) != 0ull);
;     if (active) {
;       qk_tile(kcur, qf, S, l32, hh);
;       const bool full = kb * 64 + 63 < q0;
; #pragma unroll
;     ...
;         float st[16];
; #pragma unroll
;         for (int e = 0; e < 16; ++e) {
;           const float ez = ex2(S[kt2][e]);
;           const float r = __builtin_amdgcn_rcpf(1.f + ez);
;           const bool vis = full || (kb * 64 + kt2 * 32 + crow(e, hh) < qpos);
	v_cndmask_b32_e64 v2, v2, v10, s[40:41]
	v_mul_f32_e32 v10, v4, v2
	v_mul_f32_e32 v2, v5, v2
	v_mul_f32_e32 v49, v4, v2
	v_mul_f32_e32 v2, v49, v132
	v_cndmask_b32_e64 v10, v4, v10, s[40:41]
	v_cndmask_b32_e64 v2, v49, v2, s[40:41]
	v_mul_f32_e32 v64, v13, v10
	v_mul_f32_e32 v10, v11, v10
	v_mul_f32_e32 v66, v130, v2
	v_mul_f32_e32 v2, v60, v2
	v_mul_f32_e32 v63, v63, v10
	v_mul_f32_e32 v10, v15, v10
	v_mul_f32_e32 v59, v59, v2
	v_mul_f32_e32 v2, v58, v2
	v_mul_f32_e32 v3, v3, v10
	v_mul_f32_e32 v57, v57, v2
	v_mul_f32_e32 v2, v53, v2
	v_mul_f32_e32 v13, v131, v132
	v_mul_f32_e32 v61, v61, v3
	v_mul_f32_e32 v58, v52, v2
	v_pk_mul_f32 v[2:3], v[12:13], v[48:49]
	v_pk_mul_f32 v[4:5], v[8:9], v[6:7]
	v_mul_f32_e32 v62, v62, v10
	v_pk_mul_f32 v[52:53], v[4:5], v[2:3]
	s_nop 0
	v_mov_b32_e32 v2, v52
	v_mov_b32_e32 v4, v52
	s_nop 1
	v_permlane32_swap_b32_e32 v2, v4
	v_cndmask_b32_e64 v60, v2, v4, s[40:41]
	v_mul_f32_e32 v2, v3, v7
	v_cndmask_b32_e64 v2, v3, v2, s[40:41]
	v_mul_f32_e32 v7, v129, v2
	v_mul_f32_e32 v2, v56, v2
	v_mul_f32_e32 v56, v127, v2
	v_mul_f32_e32 v2, v55, v2
	v_mul_f32_e32 v55, v125, v2
	v_mul_f32_e32 v2, v54, v2
	v_mul_f32_e32 v54, v124, v2
	v_mul_f32_e32 v2, v53, v60
	v_cndmask_b32_e64 v2, v53, v2, s[40:41]
	v_mul_f32_e32 v68, v123, v2
	v_mul_f32_e32 v2, v48, v2
	v_mul_f32_e32 v123, v117, v2
	v_mul_f32_e32 v117, v12, v2
	v_lshlrev_b32_e32 v2, 1, v113
	v_lshlrev_b32_e32 v3, 1, v120
	v_add3_u32 v12, s14, v2, v3
	v_add_u32_e32 v124, 0x2000, v12
	v_add_u32_e32 v125, 0x3000, v12
	ds_read2_b64 v[2:5], v124 offset0:128 offset1:130
	ds_read2_b64 v[8:11], v124 offset0:132 offset1:134
	ds_read2_b64 v[12:15], v125 offset0:192 offset1:194
	ds_read2_b64 v[48:51], v125 offset0:196 offset1:198
	v_mul_f32_e32 v52, v52, v60
	v_mul_f32_e32 v116, v116, v117
	v_mul_f32_e32 v6, v6, v117
	v_mul_f32_e32 v117, v52, v53
	v_mul_f32_e32 v6, v75, v6
.Lsb_join1:
	s_setprio 1
	v_cvt_pk_bf16_f32 v52, v6, v116
	v_cvt_pk_bf16_f32 v53, v123, v68
	v_cvt_pk_bf16_f32 v54, v54, v55
	v_cvt_pk_bf16_f32 v55, v56, v7
	s_waitcnt lgkmcnt(3)
	s_nop 0
	v_mfma_f32_32x32x16_bf16 v[32:47], v[2:5], v[52:55], v[32:47]
	v_cvt_pk_bf16_f32 v2, v58, v57
	v_cvt_pk_bf16_f32 v3, v59, v66
	v_cvt_pk_bf16_f32 v4, v61, v62
	v_cvt_pk_bf16_f32 v5, v63, v64
	s_waitcnt lgkmcnt(1)
	v_mfma_f32_32x32x16_bf16 v[16:31], v[12:15], v[52:55], v[16:31]
	v_mfma_f32_32x32x16_bf16 v[32:47], v[8:11], v[2:5], v[32:47]
	s_waitcnt lgkmcnt(0)
	v_mfma_f32_32x32x16_bf16 v[16:31], v[48:51], v[2:5], v[16:31]
	s_setprio 0
	ds_read2_b64 v[2:5], v124 offset0:136 offset1:138
	ds_read2_b64 v[6:9], v124 offset0:140 offset1:142
	ds_read2_b64 v[10:13], v125 offset0:200 offset1:202
	ds_read2_b64 v[48:51], v125 offset0:204 offset1:206
	s_setprio 1
	v_cvt_pk_bf16_f32 v52, v0, v65
	v_cvt_pk_bf16_f32 v53, v67, v122
	v_cvt_pk_bf16_f32 v54, v71, v69
	v_cvt_pk_bf16_f32 v55, v70, v72
	s_waitcnt lgkmcnt(3)
	s_nop 0
	v_mfma_f32_32x32x16_bf16 v[32:47], v[2:5], v[52:55], v[32:47]
	v_cvt_pk_bf16_f32 v2, v73, v74
	v_cvt_pk_bf16_f32 v3, v76, v78
	v_cvt_pk_bf16_f32 v4, v77, v79
	v_cvt_pk_bf16_f32 v5, v126, v128
	s_waitcnt lgkmcnt(1)
	v_mfma_f32_32x32x16_bf16 v[16:31], v[10:13], v[52:55], v[16:31]
	v_mfma_f32_32x32x16_bf16 v[32:47], v[6:9], v[2:5], v[32:47]
	s_waitcnt lgkmcnt(0)
	v_mfma_f32_32x32x16_bf16 v[16:31], v[48:51], v[2:5], v[16:31]
	s_setprio 0
.LBB0_488:
	s_or_b64 exec, exec, s[48:49]
	s_add_i32 s0, s10, 0xffffff81
	v_cmp_lt_i32_e32 vcc, s0, v119
	s_and_saveexec_b64 s[48:49], vcc
	s_cbranch_execz .LBB0_491
	v_cmp_lt_f32_e32 vcc, 0, v117
	s_cbranch_vccz .LBB0_491
	v_lshl_add_u32 v0, v121, 1, s14
	ds_read_b128 v[2:5], v0 offset:18432
	ds_read_b128 v[6:9], v0 offset:18464
	ds_read_b128 v[10:13], v0 offset:18496
	ds_read_b128 v[122:125], v0 offset:18528
	ds_read_b128 v[64:67], v0 offset:23040
	ds_read_b128 v[126:129], v0 offset:23072
	ds_read_b128 v[130:133], v0 offset:23104
	ds_read_b128 v[134:137], v0 offset:23136
	s_setprio 1
	s_waitcnt lgkmcnt(7)
	v_mfma_f32_32x32x16_bf16 v[48:63], v[2:5], v[80:83], 0
	s_waitcnt lgkmcnt(3)
	v_mfma_f32_32x32x16_bf16 v[64:79], v[64:67], v[80:83], 0
	v_mfma_f32_32x32x16_bf16 v[48:63], v[6:9], v[84:87], v[48:63]
	s_waitcnt lgkmcnt(2)
	v_mfma_f32_32x32x16_bf16 v[64:79], v[126:129], v[84:87], v[64:79]
	v_mfma_f32_32x32x16_bf16 v[48:63], v[10:13], v[88:91], v[48:63]
	s_waitcnt lgkmcnt(1)
	v_mfma_f32_32x32x16_bf16 v[64:79], v[130:133], v[88:91], v[64:79]
	v_mfma_f32_32x32x16_bf16 v[48:63], v[122:125], v[92:95], v[48:63]
	s_waitcnt lgkmcnt(0)
	v_mfma_f32_32x32x16_bf16 v[64:79], v[134:137], v[92:95], v[64:79]
	s_setprio 0
	s_nop 10
	v_exp_f32_e32 v0, v64
	v_add_u32_e32 v13, s10, v113
	s_sub_i32 s0, s10, 64
	v_add_u32_e32 v2, 0xffffffa1, v13
	v_cmp_lt_i32_e32 vcc, s0, v118
	s_cmp_eq_u64 vcc, exec
	s_cbranch_scc0 .Lsb_slow2
; DI float half_other(float x, int hh) { float a, b; half_swap(x, a, b); return hh ? a : b; }
; DI int crow(int reg, int hh) { return (reg & 3) + 8 * (reg >> 2) + 4 * hh; }
; DI float ex2(float x) { return __builtin_amdgcn_exp2f(x); }
; DI void sb_item(const bf16_t* __restrict__ P, const bf16_t* __restrict__ VT, bf16_t* __restrict__ Y, int item, char* lds) {
;     ...
; #pragma unroll
;         for (int e = 0; e < 16; ++e) {
;           const float ez = ex2(S[kt2][e]);
;           const float r = __builtin_amdgcn_rcpf(1.f + ez);
;           const bool vis = full || (kb * 64 + kt2 * 32 + crow(e, hh) < qpos);
;           st[e] = vis ? r : 1.f;
;           S[kt2][e] = vis ? 1.f - r : 0.f;
;         }
;         float G[4], Go[4];
; #pragma unroll
;         for (int j = 0; j < 4; ++j) { G[j] = (st[4 * j] * st[4 * j + 1]) * (st[4 * j + 2] * st[4 * j + 3]); Go[j] = half_other(G[j], hh); }
;         float T = carry;
; #pragma unroll
;         for (int j = 3; j >= 0; --j) {
;           float run = hh ? T : T * Go[j];
; #pragma unroll
;           for (int e = 3; e >= 0; --e) {
;             const int idx = 4 * j + e;
;             S[kt2][idx] *= run;
;             run *= st[idx];
;           }
;           T *= G[j] * Go[j];
;         }
;         carry = T;
	v_add_f32_e32 v0, 1.0, v0
	v_exp_f32_e32 v2, v65
	v_rcp_f32_e32 v3, v0
	v_add_f32_e32 v2, 1.0, v2
	v_sub_f32_e32 v0, 1.0, v3
	v_rcp_f32_e32 v64, v2
	v_exp_f32_e32 v4, v66
	v_sub_f32_e32 v65, 1.0, v64
	v_add_f32_e32 v2, 1.0, v4
	v_rcp_f32_e32 v66, v2
	v_exp_f32_e32 v4, v67
	v_sub_f32_e32 v67, 1.0, v66
	v_add_f32_e32 v2, 1.0, v4
	v_rcp_f32_e32 v2, v2
	v_exp_f32_e32 v4, v68
	v_mov_b32_e32 v68, v2
	v_sub_f32_e32 v122, 1.0, v2
	v_add_f32_e32 v2, 1.0, v4
	v_rcp_f32_e32 v5, v2
	v_exp_f32_e32 v4, v69
	v_sub_f32_e32 v12, 1.0, v5
	v_add_f32_e32 v2, 1.0, v4
	v_rcp_f32_e32 v14, v2
	v_exp_f32_e32 v4, v70
	v_sub_f32_e32 v15, 1.0, v14
	v_add_f32_e32 v2, 1.0, v4
	v_rcp_f32_e32 v69, v2
	v_exp_f32_e32 v4, v71
	v_sub_f32_e32 v70, 1.0, v69
	v_add_f32_e32 v2, 1.0, v4
	v_rcp_f32_e32 v71, v2
	v_exp_f32_e32 v4, v72
	v_sub_f32_e32 v72, 1.0, v71
	v_add_f32_e32 v2, 1.0, v4
	v_rcp_f32_e32 v6, v2
	v_exp_f32_e32 v4, v73
	v_sub_f32_e32 v73, 1.0, v6
	v_add_f32_e32 v2, 1.0, v4
	v_rcp_f32_e32 v8, v2
	v_exp_f32_e32 v4, v74
	v_sub_f32_e32 v74, 1.0, v8
	v_add_f32_e32 v2, 1.0, v4
	v_rcp_f32_e32 v2, v2
	v_exp_f32_e32 v4, v75
	v_mov_b32_e32 v75, v2
	v_sub_f32_e32 v123, 1.0, v2
	v_add_f32_e32 v2, 1.0, v4
	v_rcp_f32_e32 v2, v2
	v_exp_f32_e32 v4, v76
	v_mov_b32_e32 v76, v2
	v_sub_f32_e32 v124, 1.0, v2
	v_add_f32_e32 v2, 1.0, v4
	v_rcp_f32_e32 v7, v2
	v_exp_f32_e32 v4, v77
	v_sub_f32_e32 v77, 1.0, v7
	v_add_f32_e32 v2, 1.0, v4
	v_rcp_f32_e32 v2, v2
	v_exp_f32_e32 v4, v78
	v_mov_b32_e32 v78, v2
	v_sub_f32_e32 v125, 1.0, v2
	v_add_f32_e32 v2, 1.0, v4
	v_rcp_f32_e32 v2, v2
	v_exp_f32_e32 v4, v79
	v_mov_b32_e32 v79, v2
	v_sub_f32_e32 v126, 1.0, v2
	v_add_f32_e32 v2, 1.0, v4
	v_rcp_f32_e32 v127, v2
	v_mul_f32_e32 v7, v7, v78
	v_sub_f32_e32 v128, 1.0, v127
	v_mul_f32_e32 v2, v3, v64
	v_mul_f32_e32 v3, v66, v68
	v_mul_f32_e32 v4, v2, v3
	v_mov_b32_e32 v2, v4
	v_mov_b32_e32 v3, v4
	s_nop 1
	v_permlane32_swap_b32_e32 v2, v3
	v_cndmask_b32_e64 v2, v2, v3, s[40:41]
	v_mul_f32_e32 v3, v5, v14
	v_mul_f32_e32 v5, v69, v71
	v_mul_f32_e32 v3, v3, v5
	v_mov_b32_e32 v5, v3
	v_mov_b32_e32 v9, v3
	s_nop 1
	v_permlane32_swap_b32_e32 v5, v9
	v_cndmask_b32_e64 v5, v5, v9, s[40:41]
	v_mul_f32_e32 v9, v79, v127
	v_pk_mul_f32 v[6:7], v[6:7], v[8:9]
	v_mul_f32_e32 v10, v75, v76
	v_mov_b32_e32 v9, v7
	v_mov_b32_e32 v11, v7
	s_nop 1
	v_permlane32_swap_b32_e32 v9, v11
	v_cndmask_b32_e64 v11, v9, v11, s[40:41]
	v_pk_mul_f32 v[6:7], v[6:7], v[10:11]
	s_nop 0
	v_mov_b32_e32 v9, v6
	v_mov_b32_e32 v10, v6
	s_nop 1
	v_permlane32_swap_b32_e32 v9, v10
	v_cndmask_b32_e64 v116, v9, v10, s[40:41]
	v_mul_f32_e32 v9, v117, v11
	v_cndmask_b32_e64 v9, v117, v9, s[40:41]
	v_mul_f32_e32 v128, v128, v9
	v_mul_f32_e32 v9, v127, v9
	v_mul_f32_e32 v126, v126, v9
	v_mul_f32_e32 v9, v79, v9
	v_mul_f32_e32 v79, v125, v9
	v_mul_f32_e32 v9, v78, v9
	v_pk_mul_f32 v[6:7], v[6:7], v[116:117]
	v_mul_f32_e32 v77, v77, v9
	v_mul_f32_e32 v9, v7, v116
	v_pk_mul_f32 v[10:11], v[6:7], v[6:7] op_sel:[0,1] op_sel_hi:[1,0]
	v_cndmask_b32_e64 v9, v7, v9, s[40:41]
	v_mul_f32_e32 v6, v10, v5
	v_exp_f32_e32 v7, v48
	v_cndmask_b32_e64 v6, v10, v6, s[40:41]
	v_mul_f32_e32 v72, v72, v6
	v_mul_f32_e32 v6, v71, v6
	v_mul_f32_e32 v70, v70, v6
	v_mul_f32_e32 v6, v69, v6
	v_mul_f32_e32 v69, v15, v6
	v_mul_f32_e32 v6, v14, v6
	v_mul_f32_e32 v14, v3, v5
	v_add_f32_e32 v3, 1.0, v7
	v_rcp_f32_e32 v3, v3
	v_mul_f32_e32 v78, v124, v9
	v_mul_f32_e32 v9, v76, v9
	v_exp_f32_e32 v5, v49
	v_mul_f32_e32 v76, v123, v9
	v_mul_f32_e32 v9, v75, v9
	v_mul_f32_e32 v8, v8, v9
	v_mul_f32_e32 v73, v73, v8
	v_mov_b32_e32 v8, v3
	v_sub_f32_e32 v75, 1.0, v3
	v_add_f32_e32 v3, 1.0, v5
	v_rcp_f32_e32 v3, v3
	v_exp_f32_e32 v5, v50
	v_mul_f32_e32 v71, v12, v6
	v_mov_b32_e32 v6, v3
	v_sub_f32_e32 v116, 1.0, v3
	v_add_f32_e32 v3, 1.0, v5
	v_rcp_f32_e32 v12, v3
	v_exp_f32_e32 v5, v51
	v_sub_f32_e32 v117, 1.0, v12
	v_add_f32_e32 v3, 1.0, v5
	v_rcp_f32_e32 v48, v3
	v_exp_f32_e32 v5, v52
	v_sub_f32_e32 v123, 1.0, v48
	v_add_f32_e32 v3, 1.0, v5
	v_rcp_f32_e32 v7, v3
	v_exp_f32_e32 v5, v53
	v_sub_f32_e32 v124, 1.0, v7
	v_add_f32_e32 v3, 1.0, v5
	v_rcp_f32_e32 v3, v3
	v_exp_f32_e32 v5, v54
	v_mov_b32_e32 v54, v3
	v_sub_f32_e32 v125, 1.0, v3
	v_add_f32_e32 v3, 1.0, v5
	v_rcp_f32_e32 v3, v3
	v_exp_f32_e32 v5, v55
	v_mov_b32_e32 v55, v3
	v_sub_f32_e32 v127, 1.0, v3
	v_add_f32_e32 v3, 1.0, v5
	v_rcp_f32_e32 v3, v3
	v_exp_f32_e32 v5, v56
	v_mov_b32_e32 v56, v3
	v_sub_f32_e32 v129, 1.0, v3
	v_add_f32_e32 v3, 1.0, v5
	v_rcp_f32_e32 v49, v3
	v_exp_f32_e32 v5, v57
	v_sub_f32_e32 v52, 1.0, v49
	v_add_f32_e32 v3, 1.0, v5
	v_rcp_f32_e32 v53, v3
	v_exp_f32_e32 v5, v58
	v_sub_f32_e32 v57, 1.0, v53
	v_add_f32_e32 v3, 1.0, v5
	v_rcp_f32_e32 v58, v3
	v_exp_f32_e32 v5, v59
	v_sub_f32_e32 v59, 1.0, v58
	v_add_f32_e32 v3, 1.0, v5
	v_rcp_f32_e32 v3, v3
	v_exp_f32_e32 v5, v60
	v_mov_b32_e32 v60, v3
	v_sub_f32_e32 v130, 1.0, v3
	v_add_f32_e32 v3, 1.0, v5
	v_rcp_f32_e32 v5, v3
	v_mul_f32_e32 v74, v74, v9
	v_exp_f32_e32 v9, v61
	v_exp_f32_e32 v11, v62
	v_sub_f32_e32 v61, 1.0, v5
	v_add_f32_e32 v3, 1.0, v9
	v_rcp_f32_e32 v3, v3
	v_mul_f32_e32 v7, v7, v54
	v_sub_f32_e32 v62, 1.0, v3
	v_add_f32_e32 v9, 1.0, v11
	v_rcp_f32_e32 v15, v9
	v_exp_f32_e32 v11, v63
	v_sub_f32_e32 v63, 1.0, v15
	v_add_f32_e32 v9, 1.0, v11
	v_rcp_f32_e32 v11, v9
	s_nop 0
	v_sub_f32_e32 v13, 1.0, v11
	v_mul_f32_e32 v9, v55, v56
	v_mul_f32_e32 v9, v7, v9
	v_mov_b32_e32 v7, v9
	v_mov_b32_e32 v50, v9
	s_nop 1
	v_permlane32_swap_b32_e32 v7, v50
	v_cndmask_b32_e64 v7, v7, v50, s[40:41]
	v_mul_f32_e32 v49, v49, v53
	v_mul_f32_e32 v50, v58, v60
	v_mul_f32_e32 v131, v49, v50
	v_mov_b32_e32 v49, v131
	v_mov_b32_e32 v50, v131
	s_nop 1
	v_permlane32_swap_b32_e32 v49, v50
; DI float half_other(float x, int hh) { float a, b; half_swap(x, a, b); return hh ? a : b; }
; DI int crow(int reg, int hh) { return (reg & 3) + 8 * (reg >> 2) + 4 * hh; }
; DI float ex2(float x) { return __builtin_amdgcn_exp2f(x); }
; DI void sb_item(const bf16_t* __restrict__ P, const bf16_t* __restrict__ VT, bf16_t* __restrict__ Y, int item, char* lds) {
;     ...
; #pragma unroll
;         for (int e = 0; e < 16; ++e) {
;           const float ez = ex2(S[kt2][e]);
;           const float r = __builtin_amdgcn_rcpf(1.f + ez);
;           const bool vis = full || (kb * 64 + kt2 * 32 + crow(e, hh) < qpos);
;           st[e] = vis ? r : 1.f;
;           S[kt2][e] = vis ? 1.f - r : 0.f;
;         }
;         float G[4], Go[4];
; #pragma unroll
;         for (int j = 0; j < 4; ++j) { G[j] = (st[4 * j] * st[4 * j + 1]) * (st[4 * j + 2] * st[4 * j + 3]); Go[j] = half_other(G[j], hh); }
;         float T = carry;
; #pragma unroll
;         for (int j = 3; j >= 0; --j) {
;           float run = hh ? T : T * Go[j];
; #pragma unroll
;           for (int e = 3; e >= 0; --e) {
;             const int idx = 4 * j + e;
;             S[kt2][idx] *= run;
;             run *= st[idx];
;           }
;           T *= G[j] * Go[j];
;         }
;         carry = T;
;       }
;       pv_tile(kcur + TS, S, O, l32, hh);
	v_cndmask_b32_e64 v132, v49, v50, s[40:41]
	v_pk_mul_f32 v[50:51], v[14:15], v[10:11]
	v_pk_mul_f32 v[4:5], v[4:5], v[2:3]
	v_mul_f32_e32 v10, v50, v2
	v_cndmask_b32_e64 v10, v50, v10, s[40:41]
	v_mul_f32_e32 v122, v122, v10
	v_mul_f32_e32 v10, v68, v10
	v_mul_f32_e32 v67, v67, v10
	v_mul_f32_e32 v10, v66, v10
	v_mul_f32_e32 v65, v65, v10
	v_mul_f32_e32 v10, v64, v10
	v_pk_mul_f32 v[4:5], v[4:5], v[50:51]
	v_mul_f32_e32 v0, v0, v10
	v_mov_b32_e32 v2, v5
	v_mov_b32_e32 v10, v5
	s_nop 1
	v_permlane32_swap_b32_e32 v2, v10
	v_cndmask_b32_e64 v2, v2, v10, s[40:41]
	v_mul_f32_e32 v10, v4, v2
	v_mul_f32_e32 v2, v5, v2
	v_mul_f32_e32 v49, v4, v2
	v_mul_f32_e32 v2, v49, v132
	v_cndmask_b32_e64 v10, v4, v10, s[40:41]
	v_cndmask_b32_e64 v2, v49, v2, s[40:41]
	v_mul_f32_e32 v64, v13, v10
	v_mul_f32_e32 v10, v11, v10
	v_mul_f32_e32 v66, v130, v2
	v_mul_f32_e32 v2, v60, v2
	v_mul_f32_e32 v63, v63, v10
	v_mul_f32_e32 v10, v15, v10
	v_mul_f32_e32 v59, v59, v2
	v_mul_f32_e32 v2, v58, v2
	v_mul_f32_e32 v3, v3, v10
	v_mul_f32_e32 v57, v57, v2
	v_mul_f32_e32 v2, v53, v2
	v_mul_f32_e32 v13, v131, v132
	v_mul_f32_e32 v61, v61, v3
	v_mul_f32_e32 v58, v52, v2
	v_pk_mul_f32 v[2:3], v[12:13], v[48:49]
	v_pk_mul_f32 v[4:5], v[8:9], v[6:7]
	v_mul_f32_e32 v62, v62, v10
	v_pk_mul_f32 v[52:53], v[4:5], v[2:3]
	s_nop 0
	v_mov_b32_e32 v2, v52
	v_mov_b32_e32 v4, v52
	s_nop 1
	v_permlane32_swap_b32_e32 v2, v4
	v_cndmask_b32_e64 v60, v2, v4, s[40:41]
	v_mul_f32_e32 v2, v3, v7
	v_cndmask_b32_e64 v2, v3, v2, s[40:41]
	v_mul_f32_e32 v7, v129, v2
	v_mul_f32_e32 v2, v56, v2
	v_mul_f32_e32 v56, v127, v2
	v_mul_f32_e32 v2, v55, v2
	v_mul_f32_e32 v55, v125, v2
	v_mul_f32_e32 v2, v54, v2
	v_mul_f32_e32 v54, v124, v2
	v_mul_f32_e32 v2, v53, v60
	v_cndmask_b32_e64 v2, v53, v2, s[40:41]
	v_mul_f32_e32 v68, v123, v2
	v_mul_f32_e32 v2, v48, v2
	v_mul_f32_e32 v123, v117, v2
	v_mul_f32_e32 v117, v12, v2
	v_lshlrev_b32_e32 v2, 1, v113
	v_lshlrev_b32_e32 v3, 1, v120
	v_add3_u32 v12, s14, v2, v3
	v_add_u32_e32 v124, 0x6800, v12
	v_add_u32_e32 v125, 0x7800, v12
	ds_read2_b64 v[2:5], v124 offset0:128 offset1:130
	ds_read2_b64 v[8:11], v124 offset0:132 offset1:134
	ds_read2_b64 v[12:15], v125 offset0:192 offset1:194
	ds_read2_b64 v[48:51], v125 offset0:196 offset1:198
	v_mul_f32_e32 v52, v52, v60
	v_mul_f32_e32 v116, v116, v117
	v_mul_f32_e32 v6, v6, v117
	v_mul_f32_e32 v117, v52, v53
	v_mul_f32_e32 v6, v75, v6
	s_branch .Lsb_join2
.Lsb_slow2:
	v_add_f32_e32 v0, 1.0, v0
	v_cmp_lt_i32_e64 s[0:1], v2, v112
	v_exp_f32_e32 v2, v65
	v_rcp_f32_e32 v0, v0
	s_or_b64 s[0:1], vcc, s[0:1]
	v_add_u32_e32 v4, 0xffffffa2, v13
	v_add_f32_e32 v2, 1.0, v2
	v_cndmask_b32_e64 v3, 1.0, v0, s[0:1]
	v_sub_f32_e32 v0, 1.0, v0
	v_rcp_f32_e32 v2, v2
	v_cndmask_b32_e64 v0, 0, v0, s[0:1]
	v_cmp_lt_i32_e64 s[0:1], v4, v112
	v_exp_f32_e32 v4, v66
	s_or_b64 s[0:1], vcc, s[0:1]
	v_cndmask_b32_e64 v64, 1.0, v2, s[0:1]
	v_sub_f32_e32 v2, 1.0, v2
	v_cndmask_b32_e64 v65, 0, v2, s[0:1]
	v_add_f32_e32 v2, 1.0, v4
	v_rcp_f32_e32 v2, v2
	v_add_u32_e32 v4, 0xffffffa3, v13
	v_cmp_lt_i32_e64 s[0:1], v4, v112
	v_exp_f32_e32 v4, v67
	s_or_b64 s[0:1], vcc, s[0:1]
	v_cndmask_b32_e64 v66, 1.0, v2, s[0:1]
	v_sub_f32_e32 v2, 1.0, v2
	v_cndmask_b32_e64 v67, 0, v2, s[0:1]
	v_add_f32_e32 v2, 1.0, v4
	v_rcp_f32_e32 v2, v2
	v_add_u32_e32 v4, 0xffffffa4, v13
	v_cmp_lt_i32_e64 s[0:1], v4, v112
	v_exp_f32_e32 v4, v68
	s_or_b64 s[0:1], vcc, s[0:1]
	v_cndmask_b32_e64 v68, 1.0, v2, s[0:1]
	v_sub_f32_e32 v2, 1.0, v2
	v_cndmask_b32_e64 v122, 0, v2, s[0:1]
	v_add_f32_e32 v2, 1.0, v4
	v_rcp_f32_e32 v2, v2
	v_add_u32_e32 v4, 0xffffffa9, v13
	v_cmp_lt_i32_e64 s[0:1], v4, v112
	v_exp_f32_e32 v4, v69
	s_or_b64 s[0:1], vcc, s[0:1]
	v_cndmask_b32_e64 v5, 1.0, v2, s[0:1]
	v_sub_f32_e32 v2, 1.0, v2
	v_cndmask_b32_e64 v12, 0, v2, s[0:1]
	v_add_f32_e32 v2, 1.0, v4
	v_rcp_f32_e32 v2, v2
	v_add_u32_e32 v4, 0xffffffaa, v13
	v_cmp_lt_i32_e64 s[0:1], v4, v112
	v_exp_f32_e32 v4, v70
	s_or_b64 s[0:1], vcc, s[0:1]
	v_cndmask_b32_e64 v14, 1.0, v2, s[0:1]
	v_sub_f32_e32 v2, 1.0, v2
	v_cndmask_b32_e64 v15, 0, v2, s[0:1]
	v_add_f32_e32 v2, 1.0, v4
	v_rcp_f32_e32 v2, v2
	v_add_u32_e32 v4, 0xffffffab, v13
	v_cmp_lt_i32_e64 s[0:1], v4, v112
	v_exp_f32_e32 v4, v71
	s_or_b64 s[0:1], vcc, s[0:1]
	v_cndmask_b32_e64 v69, 1.0, v2, s[0:1]
	v_sub_f32_e32 v2, 1.0, v2
	v_cndmask_b32_e64 v70, 0, v2, s[0:1]
	v_add_f32_e32 v2, 1.0, v4
	v_rcp_f32_e32 v2, v2
	v_add_u32_e32 v4, 0xffffffac, v13
	v_cmp_lt_i32_e64 s[0:1], v4, v112
	v_exp_f32_e32 v4, v72
	s_or_b64 s[0:1], vcc, s[0:1]
	v_cndmask_b32_e64 v71, 1.0, v2, s[0:1]
	v_sub_f32_e32 v2, 1.0, v2
	v_cndmask_b32_e64 v72, 0, v2, s[0:1]
	v_add_f32_e32 v2, 1.0, v4
	v_rcp_f32_e32 v2, v2
	v_add_u32_e32 v4, 0xffffffb1, v13
	v_cmp_lt_i32_e64 s[0:1], v4, v112
	v_exp_f32_e32 v4, v73
	s_or_b64 s[0:1], vcc, s[0:1]
	v_cndmask_b32_e64 v6, 1.0, v2, s[0:1]
	v_sub_f32_e32 v2, 1.0, v2
	v_cndmask_b32_e64 v73, 0, v2, s[0:1]
	v_add_f32_e32 v2, 1.0, v4
	v_rcp_f32_e32 v2, v2
	v_add_u32_e32 v4, 0xffffffb2, v13
	v_cmp_lt_i32_e64 s[0:1], v4, v112
	v_exp_f32_e32 v4, v74
	s_or_b64 s[0:1], vcc, s[0:1]
	v_cndmask_b32_e64 v8, 1.0, v2, s[0:1]
	v_sub_f32_e32 v2, 1.0, v2
	v_cndmask_b32_e64 v74, 0, v2, s[0:1]
	v_add_f32_e32 v2, 1.0, v4
	v_rcp_f32_e32 v2, v2
	v_add_u32_e32 v4, 0xffffffb3, v13
	v_cmp_lt_i32_e64 s[0:1], v4, v112
	v_exp_f32_e32 v4, v75
	s_or_b64 s[0:1], vcc, s[0:1]
	v_cndmask_b32_e64 v75, 1.0, v2, s[0:1]
	v_sub_f32_e32 v2, 1.0, v2
	v_cndmask_b32_e64 v123, 0, v2, s[0:1]
	v_add_f32_e32 v2, 1.0, v4
	v_rcp_f32_e32 v2, v2
	v_add_u32_e32 v4, 0xffffffb4, v13
	v_cmp_lt_i32_e64 s[0:1], v4, v112
	v_exp_f32_e32 v4, v76
	s_or_b64 s[0:1], vcc, s[0:1]
	v_cndmask_b32_e64 v76, 1.0, v2, s[0:1]
; DI float half_other(float x, int hh) { float a, b; half_swap(x, a, b); return hh ? a : b; }
; DI int crow(int reg, int hh) { return (reg & 3) + 8 * (reg >> 2) + 4 * hh; }
; DI float ex2(float x) { return __builtin_amdgcn_exp2f(x); }
; DI void sb_item(const bf16_t* __restrict__ P, const bf16_t* __restrict__ VT, bf16_t* __restrict__ Y, int item, char* lds) {
;     ...
; #pragma unroll
;         for (int e = 0; e < 16; ++e) {
;           const float ez = ex2(S[kt2][e]);
;           const float r = __builtin_amdgcn_rcpf(1.f + ez);
;           const bool vis = full || (kb * 64 + kt2 * 32 + crow(e, hh) < qpos);
;           st[e] = vis ? r : 1.f;
;           S[kt2][e] = vis ? 1.f - r : 0.f;
;         }
;         float G[4], Go[4];
; #pragma unroll
;         for (int j = 0; j < 4; ++j) { G[j] = (st[4 * j] * st[4 * j + 1]) * (st[4 * j + 2] * st[4 * j + 3]); Go[j] = half_other(G[j], hh); }
;         float T = carry;
; #pragma unroll
;         for (int j = 3; j >= 0; --j) {
;           float run = hh ? T : T * Go[j];
; #pragma unroll
;           for (int e = 3; e >= 0; --e) {
;             const int idx = 4 * j + e;
;             S[kt2][idx] *= run;
;             run *= st[idx];
;           }
;           T *= G[j] * Go[j];
;         }
;         carry = T;
	v_sub_f32_e32 v2, 1.0, v2
	v_cndmask_b32_e64 v124, 0, v2, s[0:1]
	v_add_f32_e32 v2, 1.0, v4
	v_rcp_f32_e32 v2, v2
	v_add_u32_e32 v4, 0xffffffb9, v13
	v_cmp_lt_i32_e64 s[0:1], v4, v112
	v_exp_f32_e32 v4, v77
	s_or_b64 s[0:1], vcc, s[0:1]
	v_cndmask_b32_e64 v7, 1.0, v2, s[0:1]
	v_sub_f32_e32 v2, 1.0, v2
	v_cndmask_b32_e64 v77, 0, v2, s[0:1]
	v_add_f32_e32 v2, 1.0, v4
	v_rcp_f32_e32 v2, v2
	v_add_u32_e32 v4, 0xffffffba, v13
	v_cmp_lt_i32_e64 s[0:1], v4, v112
	v_exp_f32_e32 v4, v78
	s_or_b64 s[0:1], vcc, s[0:1]
	v_cndmask_b32_e64 v78, 1.0, v2, s[0:1]
	v_sub_f32_e32 v2, 1.0, v2
	v_cndmask_b32_e64 v125, 0, v2, s[0:1]
	v_add_f32_e32 v2, 1.0, v4
	v_rcp_f32_e32 v2, v2
	v_add_u32_e32 v4, 0xffffffbb, v13
	v_cmp_lt_i32_e64 s[0:1], v4, v112
	v_exp_f32_e32 v4, v79
	s_or_b64 s[0:1], vcc, s[0:1]
	v_cndmask_b32_e64 v79, 1.0, v2, s[0:1]
	v_sub_f32_e32 v2, 1.0, v2
	v_cndmask_b32_e64 v126, 0, v2, s[0:1]
	v_add_f32_e32 v2, 1.0, v4
	v_rcp_f32_e32 v2, v2
	v_add_u32_e32 v4, 0xffffffbc, v13
	v_cmp_lt_i32_e64 s[0:1], v4, v112
	s_or_b64 s[0:1], vcc, s[0:1]
	v_mul_f32_e32 v7, v7, v78
	v_cndmask_b32_e64 v127, 1.0, v2, s[0:1]
	v_sub_f32_e32 v2, 1.0, v2
	v_cndmask_b32_e64 v128, 0, v2, s[0:1]
	v_mul_f32_e32 v2, v3, v64
	v_mul_f32_e32 v3, v66, v68
	v_mul_f32_e32 v4, v2, v3
	v_mov_b32_e32 v2, v4
	v_mov_b32_e32 v3, v4
	s_nop 1
	v_permlane32_swap_b32_e32 v2, v3
	v_cndmask_b32_e64 v2, v2, v3, s[40:41]
	v_mul_f32_e32 v3, v5, v14
	v_mul_f32_e32 v5, v69, v71
	v_mul_f32_e32 v3, v3, v5
	v_mov_b32_e32 v5, v3
	v_mov_b32_e32 v9, v3
	s_nop 1
	v_permlane32_swap_b32_e32 v5, v9
	v_cndmask_b32_e64 v5, v5, v9, s[40:41]
	v_mul_f32_e32 v9, v79, v127
	v_pk_mul_f32 v[6:7], v[6:7], v[8:9]
	v_mul_f32_e32 v10, v75, v76
	v_mov_b32_e32 v9, v7
	v_mov_b32_e32 v11, v7
	s_nop 1
	v_permlane32_swap_b32_e32 v9, v11
	v_cndmask_b32_e64 v11, v9, v11, s[40:41]
	v_pk_mul_f32 v[6:7], v[6:7], v[10:11]
	s_nop 0
	v_mov_b32_e32 v9, v6
	v_mov_b32_e32 v10, v6
	s_nop 1
	v_permlane32_swap_b32_e32 v9, v10
	v_cndmask_b32_e64 v116, v9, v10, s[40:41]
	v_mul_f32_e32 v9, v117, v11
	v_cndmask_b32_e64 v9, v117, v9, s[40:41]
	v_mul_f32_e32 v128, v128, v9
	v_mul_f32_e32 v9, v127, v9
	v_mul_f32_e32 v126, v126, v9
	v_mul_f32_e32 v9, v79, v9
	v_mul_f32_e32 v79, v125, v9
	v_mul_f32_e32 v9, v78, v9
	v_pk_mul_f32 v[6:7], v[6:7], v[116:117]
	v_mul_f32_e32 v77, v77, v9
	v_mul_f32_e32 v9, v7, v116
	v_pk_mul_f32 v[10:11], v[6:7], v[6:7] op_sel:[0,1] op_sel_hi:[1,0]
	v_cndmask_b32_e64 v9, v7, v9, s[40:41]
	v_mul_f32_e32 v6, v10, v5
	v_exp_f32_e32 v7, v48
	v_cndmask_b32_e64 v6, v10, v6, s[40:41]
	v_mul_f32_e32 v72, v72, v6
	v_mul_f32_e32 v6, v71, v6
	v_mul_f32_e32 v70, v70, v6
	v_mul_f32_e32 v6, v69, v6
	v_mul_f32_e32 v69, v15, v6
	v_mul_f32_e32 v6, v14, v6
	v_mul_f32_e32 v14, v3, v5
	v_add_f32_e32 v3, 1.0, v7
	v_rcp_f32_e32 v3, v3
	v_add_u32_e32 v5, 0xffffff81, v13
	v_mul_f32_e32 v78, v124, v9
	v_mul_f32_e32 v9, v76, v9
	v_cmp_lt_i32_e64 s[0:1], v5, v112
	v_exp_f32_e32 v5, v49
	v_mul_f32_e32 v76, v123, v9
	v_mul_f32_e32 v9, v75, v9
	v_mul_f32_e32 v8, v8, v9
	s_or_b64 s[0:1], vcc, s[0:1]
	v_mul_f32_e32 v73, v73, v8
	v_cndmask_b32_e64 v8, 1.0, v3, s[0:1]
	v_sub_f32_e32 v3, 1.0, v3
	v_cndmask_b32_e64 v75, 0, v3, s[0:1]
	v_add_f32_e32 v3, 1.0, v5
	v_rcp_f32_e32 v3, v3
	v_add_u32_e32 v5, 0xffffff82, v13
	v_cmp_lt_i32_e64 s[0:1], v5, v112
	v_exp_f32_e32 v5, v50
	s_or_b64 s[0:1], vcc, s[0:1]
	v_mul_f32_e32 v71, v12, v6
	v_cndmask_b32_e64 v6, 1.0, v3, s[0:1]
	v_sub_f32_e32 v3, 1.0, v3
	v_cndmask_b32_e64 v116, 0, v3, s[0:1]
	v_add_f32_e32 v3, 1.0, v5
	v_rcp_f32_e32 v3, v3
	v_add_u32_e32 v5, 0xffffff83, v13
	v_cmp_lt_i32_e64 s[0:1], v5, v112
	v_exp_f32_e32 v5, v51
	s_or_b64 s[0:1], vcc, s[0:1]
	v_cndmask_b32_e64 v12, 1.0, v3, s[0:1]
	v_sub_f32_e32 v3, 1.0, v3
	v_cndmask_b32_e64 v117, 0, v3, s[0:1]
	v_add_f32_e32 v3, 1.0, v5
	v_rcp_f32_e32 v3, v3
	v_add_u32_e32 v5, 0xffffff84, v13
	v_cmp_lt_i32_e64 s[0:1], v5, v112
	v_exp_f32_e32 v5, v52
	s_or_b64 s[0:1], vcc, s[0:1]
	v_cndmask_b32_e64 v48, 1.0, v3, s[0:1]
	v_sub_f32_e32 v3, 1.0, v3
	v_cndmask_b32_e64 v123, 0, v3, s[0:1]
	v_add_f32_e32 v3, 1.0, v5
	v_rcp_f32_e32 v3, v3
	v_add_u32_e32 v5, 0xffffff89, v13
	v_cmp_lt_i32_e64 s[0:1], v5, v112
	v_exp_f32_e32 v5, v53
	s_or_b64 s[0:1], vcc, s[0:1]
	v_cndmask_b32_e64 v7, 1.0, v3, s[0:1]
	v_sub_f32_e32 v3, 1.0, v3
	v_cndmask_b32_e64 v124, 0, v3, s[0:1]
	v_add_f32_e32 v3, 1.0, v5
	v_rcp_f32_e32 v3, v3
	v_add_u32_e32 v5, 0xffffff8a, v13
	v_cmp_lt_i32_e64 s[0:1], v5, v112
	v_exp_f32_e32 v5, v54
	s_or_b64 s[0:1], vcc, s[0:1]
	v_cndmask_b32_e64 v54, 1.0, v3, s[0:1]
	v_sub_f32_e32 v3, 1.0, v3
	v_cndmask_b32_e64 v125, 0, v3, s[0:1]
	v_add_f32_e32 v3, 1.0, v5
	v_rcp_f32_e32 v3, v3
	v_add_u32_e32 v5, 0xffffff8b, v13
	v_cmp_lt_i32_e64 s[0:1], v5, v112
	v_exp_f32_e32 v5, v55
	s_or_b64 s[0:1], vcc, s[0:1]
	v_cndmask_b32_e64 v55, 1.0, v3, s[0:1]
	v_sub_f32_e32 v3, 1.0, v3
	v_cndmask_b32_e64 v127, 0, v3, s[0:1]
	v_add_f32_e32 v3, 1.0, v5
	v_rcp_f32_e32 v3, v3
	v_add_u32_e32 v5, 0xffffff8c, v13
	v_cmp_lt_i32_e64 s[0:1], v5, v112
	v_exp_f32_e32 v5, v56
	s_or_b64 s[0:1], vcc, s[0:1]
	v_cndmask_b32_e64 v56, 1.0, v3, s[0:1]
; DI float half_other(float x, int hh) { float a, b; half_swap(x, a, b); return hh ? a : b; }
; DI void sb_item(const bf16_t* __restrict__ P, const bf16_t* __restrict__ VT, bf16_t* __restrict__ Y, int item, char* lds) {
;     ...
;         float G[4], Go[4];
; #pragma unroll
;         for (int j = 0; j < 4; ++j) { G[j] = (st[4 * j] * st[4 * j + 1]) * (st[4 * j + 2] * st[4 * j + 3]); Go[j] = half_other(G[j], hh); }
;         float T = carry;
; #pragma unroll
;         for (int j = 3; j >= 0; --j) {
;           float run = hh ? T : T * Go[j];
; #pragma unroll
;           for (int e = 3; e >= 0; --e) {
;             const int idx = 4 * j + e;
;             S[kt2][idx] *= run;
;             run *= st[idx];
;           }
;           T *= G[j] * Go[j];
;         }
;         carry = T;
;       }
;       pv_tile(kcur + TS, S, O, l32, hh);
	v_sub_f32_e32 v3, 1.0, v3
	v_cndmask_b32_e64 v129, 0, v3, s[0:1]
	v_add_f32_e32 v3, 1.0, v5
	v_rcp_f32_e32 v3, v3
	v_add_u32_e32 v5, 0xffffff91, v13
	v_cmp_lt_i32_e64 s[0:1], v5, v112
	v_exp_f32_e32 v5, v57
	s_or_b64 s[0:1], vcc, s[0:1]
	v_cndmask_b32_e64 v49, 1.0, v3, s[0:1]
	v_sub_f32_e32 v3, 1.0, v3
	v_cndmask_b32_e64 v52, 0, v3, s[0:1]
	v_add_f32_e32 v3, 1.0, v5
	v_rcp_f32_e32 v3, v3
	v_add_u32_e32 v5, 0xffffff92, v13
	v_cmp_lt_i32_e64 s[0:1], v5, v112
	v_exp_f32_e32 v5, v58
	s_or_b64 s[0:1], vcc, s[0:1]
	v_cndmask_b32_e64 v53, 1.0, v3, s[0:1]
	v_sub_f32_e32 v3, 1.0, v3
	v_cndmask_b32_e64 v57, 0, v3, s[0:1]
	v_add_f32_e32 v3, 1.0, v5
	v_rcp_f32_e32 v3, v3
	v_add_u32_e32 v5, 0xffffff93, v13
	v_cmp_lt_i32_e64 s[0:1], v5, v112
	v_exp_f32_e32 v5, v59
	s_or_b64 s[0:1], vcc, s[0:1]
	v_cndmask_b32_e64 v58, 1.0, v3, s[0:1]
	v_sub_f32_e32 v3, 1.0, v3
	v_cndmask_b32_e64 v59, 0, v3, s[0:1]
	v_add_f32_e32 v3, 1.0, v5
	v_rcp_f32_e32 v3, v3
	v_add_u32_e32 v5, 0xffffff94, v13
	v_cmp_lt_i32_e64 s[0:1], v5, v112
	v_exp_f32_e32 v5, v60
	s_or_b64 s[0:1], vcc, s[0:1]
	v_cndmask_b32_e64 v60, 1.0, v3, s[0:1]
	v_sub_f32_e32 v3, 1.0, v3
	v_cndmask_b32_e64 v130, 0, v3, s[0:1]
	v_add_f32_e32 v3, 1.0, v5
	v_rcp_f32_e32 v3, v3
	v_mul_f32_e32 v74, v74, v9
	v_add_u32_e32 v5, 0xffffff99, v13
	v_exp_f32_e32 v9, v61
	v_cmp_lt_i32_e64 s[0:1], v5, v112
	s_or_b64 s[0:1], vcc, s[0:1]
	v_exp_f32_e32 v11, v62
	v_cndmask_b32_e64 v5, 1.0, v3, s[0:1]
	v_sub_f32_e32 v3, 1.0, v3
	v_cndmask_b32_e64 v61, 0, v3, s[0:1]
	v_add_f32_e32 v3, 1.0, v9
	v_rcp_f32_e32 v9, v3
	v_add_u32_e32 v3, 0xffffff9a, v13
	v_cmp_lt_i32_e64 s[0:1], v3, v112
	s_or_b64 s[0:1], vcc, s[0:1]
	v_mul_f32_e32 v7, v7, v54
	v_cndmask_b32_e64 v3, 1.0, v9, s[0:1]
	v_sub_f32_e32 v9, 1.0, v9
	v_cndmask_b32_e64 v62, 0, v9, s[0:1]
	v_add_f32_e32 v9, 1.0, v11
	v_rcp_f32_e32 v9, v9
	v_add_u32_e32 v11, 0xffffff9b, v13
	v_cmp_lt_i32_e64 s[0:1], v11, v112
	v_exp_f32_e32 v11, v63
	s_or_b64 s[0:1], vcc, s[0:1]
	v_cndmask_b32_e64 v15, 1.0, v9, s[0:1]
	v_sub_f32_e32 v9, 1.0, v9
	v_cndmask_b32_e64 v63, 0, v9, s[0:1]
	v_add_f32_e32 v9, 1.0, v11
	v_rcp_f32_e32 v9, v9
	v_add_u32_e32 v11, 0xffffff9c, v13
	v_cmp_lt_i32_e64 s[0:1], v11, v112
	s_or_b64 vcc, vcc, s[0:1]
	v_cndmask_b32_e32 v11, 1.0, v9, vcc
	v_sub_f32_e32 v9, 1.0, v9
	v_cndmask_b32_e32 v13, 0, v9, vcc
	v_mul_f32_e32 v9, v55, v56
	v_mul_f32_e32 v9, v7, v9
	v_mov_b32_e32 v7, v9
	v_mov_b32_e32 v50, v9
	s_nop 1
	v_permlane32_swap_b32_e32 v7, v50
	v_cndmask_b32_e64 v7, v7, v50, s[40:41]
	v_mul_f32_e32 v49, v49, v53
	v_mul_f32_e32 v50, v58, v60
	v_mul_f32_e32 v131, v49, v50
	v_mov_b32_e32 v49, v131
	v_mov_b32_e32 v50, v131
	s_nop 1
	v_permlane32_swap_b32_e32 v49, v50
	v_cndmask_b32_e64 v132, v49, v50, s[40:41]
	v_pk_mul_f32 v[50:51], v[14:15], v[10:11]
	v_pk_mul_f32 v[4:5], v[4:5], v[2:3]
	v_mul_f32_e32 v10, v50, v2
	v_cndmask_b32_e64 v10, v50, v10, s[40:41]
	v_mul_f32_e32 v122, v122, v10
	v_mul_f32_e32 v10, v68, v10
	v_mul_f32_e32 v67, v67, v10
	v_mul_f32_e32 v10, v66, v10
	v_mul_f32_e32 v65, v65, v10
	v_mul_f32_e32 v10, v64, v10
	v_pk_mul_f32 v[4:5], v[4:5], v[50:51]
	v_mul_f32_e32 v0, v0, v10
	v_mov_b32_e32 v2, v5
	v_mov_b32_e32 v10, v5
	s_nop 1
	v_permlane32_swap_b32_e32 v2, v10
	v_cndmask_b32_e64 v2, v2, v10, s[40:41]
	v_mul_f32_e32 v10, v4, v2
	v_mul_f32_e32 v2, v5, v2
	v_mul_f32_e32 v49, v4, v2
	v_mul_f32_e32 v2, v49, v132
	v_cndmask_b32_e64 v10, v4, v10, s[40:41]
	v_cndmask_b32_e64 v2, v49, v2, s[40:41]
	v_mul_f32_e32 v64, v13, v10
	v_mul_f32_e32 v10, v11, v10
	v_mul_f32_e32 v66, v130, v2
	v_mul_f32_e32 v2, v60, v2
	v_mul_f32_e32 v63, v63, v10
	v_mul_f32_e32 v10, v15, v10
	v_mul_f32_e32 v59, v59, v2
	v_mul_f32_e32 v2, v58, v2
	v_mul_f32_e32 v3, v3, v10
	v_mul_f32_e32 v57, v57, v2
	v_mul_f32_e32 v2, v53, v2
	v_mul_f32_e32 v13, v131, v132
	v_mul_f32_e32 v61, v61, v3
	v_mul_f32_e32 v58, v52, v2
	v_pk_mul_f32 v[2:3], v[12:13], v[48:49]
	v_pk_mul_f32 v[4:5], v[8:9], v[6:7]
	v_mul_f32_e32 v62, v62, v10
	v_pk_mul_f32 v[52:53], v[4:5], v[2:3]
	s_nop 0
	v_mov_b32_e32 v2, v52
	v_mov_b32_e32 v4, v52
	s_nop 1
	v_permlane32_swap_b32_e32 v2, v4
	v_cndmask_b32_e64 v60, v2, v4, s[40:41]
	v_mul_f32_e32 v2, v3, v7
	v_cndmask_b32_e64 v2, v3, v2, s[40:41]
	v_mul_f32_e32 v7, v129, v2
	v_mul_f32_e32 v2, v56, v2
	v_mul_f32_e32 v56, v127, v2
	v_mul_f32_e32 v2, v55, v2
	v_mul_f32_e32 v55, v125, v2
	v_mul_f32_e32 v2, v54, v2
	v_mul_f32_e32 v54, v124, v2
	v_mul_f32_e32 v2, v53, v60
	v_cndmask_b32_e64 v2, v53, v2, s[40:41]
	v_mul_f32_e32 v68, v123, v2
	v_mul_f32_e32 v2, v48, v2
	v_mul_f32_e32 v123, v117, v2
	v_mul_f32_e32 v117, v12, v2
	v_lshlrev_b32_e32 v2, 1, v113
	v_lshlrev_b32_e32 v3, 1, v120
	v_add3_u32 v12, s14, v2, v3
	v_add_u32_e32 v124, 0x6800, v12
	v_add_u32_e32 v125, 0x7800, v12
	ds_read2_b64 v[2:5], v124 offset0:128 offset1:130
	ds_read2_b64 v[8:11], v124 offset0:132 offset1:134
	ds_read2_b64 v[12:15], v125 offset0:192 offset1:194
	ds_read2_b64 v[48:51], v125 offset0:196 offset1:198
	v_mul_f32_e32 v52, v52, v60
	v_mul_f32_e32 v116, v116, v117
	v_mul_f32_e32 v6, v6, v117
	v_mul_f32_e32 v117, v52, v53
	v_mul_f32_e32 v6, v75, v6
